# attention K/V LDS-DMA addresses via per-job scalar base + 32-bit lane offset (2 VALU per key-row group instead of 4 64-bit ops); masks on 4 rotating lane masks
# speedup vs baseline: 1.0047x; 1.0005x over previous
; #define LAS __attribute__((address_space(3)))
; #define ATT_LOAD_Q(dst, J, set) do { const int qp_ = (J).pos0 + (32 * (set) + qc) * (J).d; _Pragma("unroll") for (int kk_ = 0; kk_ < 4; ++kk_) dst[kk_] = gld<bf16x8>(Qa + ((J).hb + (size_t)qp_) * 64 + 8 * h + 16 * kk_); } while (0)
; __device__ __forceinline__ void att_phase(unsigned char* ws, LAS unsigned char* lds, int lane, int wave, int G) {
;     ...
;     LAS unsigned char* vlds = lds + wave * 16384;
;     const int nun = G == 256 ? 2 : (512 + G - 1) / G;
;     const int qc = lane & 31, h = lane >> 5;
;     const int i16 = lane & 15, tq = i16 >> 2, tp = i16 & 3, blk = (lane >> 4) & 1;
;     LAS const unsigned char* trb = vlds + (4 * h + tq) * VP + (16 * blk) * 2 + 8 * tp;
;     bf16x8 qfA[4], qfB[4];
;     ...
;     LAS const unsigned char* kfb = vlds + qc * 128;
;     AttJob P, N;
;     bool have = att_params(0, nun, G, wave, P);
;     int sb = 0;
;     if (have) { ATT_DMA_KV(P, 0, 0); ATT_LOAD_Q(qfA, P, 0); ATT_LOAD_Q(qfB, P, 1); }
; #pragma unroll 1
;     for (int q = 0; have; ++q) {
;         const bool hn = att_params(q + 1, nun, G, wave, N);
;         const int pos0 = P.pos0, d = P.d, brmode = P.brmode;
;         bf16* OPh = (bf16*)OP + P.hb * 64; float* MLh = ML + P.hb * 2; bf16* outp = MO + (size_t)P.b * SEQ * 1024 + P.head * 64;
;         float mA = -1e30f, lA = 0.f, mB = -1e30f, lB = 0.f;
;         f32x16 oA0, oA1, oB0, oB1;
; #pragma unroll
;         for (int i = 0; i < 16; ++i) { oA0[i] = 0.f; oA1[i] = 0.f; oB0[i] = 0.f; oB1[i] = 0.f; }
;         int kminA = 0, kminB = 0;
;         { const int t0 = 128 * d - pos0; if (t0 > 0) kminA = (t0 + d - 1) / d; const int t1 = 96 * d - pos0; if (t1 > 0) kminB = (t1 + d - 1) / d; }
;         const int mloA = qc > kminA ? qc : kminA, mloB = qc > kminB ? qc : kminB;
; #pragma unroll
.LBB0_58:
	s_and_b64 vcc, exec, s[0:1]
	s_cbranch_vccnz .LBB0_118
	v_ashrrev_i32_e32 v191, 3, v0
	v_xor_b32_e32 v2, v191, v0
	v_lshlrev_b32_e32 v2, 4, v2
	v_and_b32_e32 v164, 0x70, v2
	v_lshl_add_u64 v[2:3], s[68:69], 0, v[164:165]
	s_mov_b64 s[0:1], 0x13000000
	v_lshl_add_u32 v6, v191, 4, s11
	v_lshl_add_u64 v[180:181], v[2:3], 0, s[0:1]
	v_lshlrev_b32_e32 v2, 4, v0
	v_add_u32_e32 v4, 0xfffff800, v6
	v_and_b32_e32 v164, 0x70, v2
	s_add_u32 s38, s68, 0x33000000
	v_lshl_add_u64 v[2:3], s[68:69], 0, v[164:165]
	s_mov_b64 s[0:1], 0x17000000
	v_max_i32_e32 v164, 0, v4
	s_addc_u32 s41, s69, 0
	v_lshl_add_u64 v[182:183], v[2:3], 0, s[0:1]
	v_lshl_add_u64 v[2:3], s[12:13], 0, v[164:165]
	s_add_u32 s42, s68, 0x800000
	v_lshlrev_b64 v[2:3], 7, v[2:3]
	s_mov_b32 m0, s33
	s_addc_u32 s43, s69, 0
	v_lshl_add_u64 v[4:5], v[180:181], 0, v[2:3]
	s_add_i32 s44, s33, 0x2000
	global_load_lds_dwordx4 v[4:5], off
	v_lshl_add_u64 v[2:3], v[182:183], 0, v[2:3]
	s_mov_b32 m0, s44
	s_add_i32 s48, s33, 0x800
	global_load_lds_dwordx4 v[2:3], off
	v_add_u32_e32 v2, 0xfffff880, v6
	v_max_i32_e32 v164, 0, v2
	v_lshl_add_u64 v[2:3], s[12:13], 0, v[164:165]
	v_lshlrev_b64 v[2:3], 7, v[2:3]
	v_lshl_add_u64 v[4:5], v[180:181], 0, v[2:3]
	s_mov_b32 m0, s66
	v_lshl_add_u64 v[2:3], v[182:183], 0, v[2:3]
	global_load_lds_dwordx4 v[4:5], off
	s_mov_b32 m0, s67
	s_add_i32 s49, s33, 0x2800
	global_load_lds_dwordx4 v[2:3], off
	v_add_u32_e32 v2, 0xfffff900, v6
	v_max_i32_e32 v164, 0, v2
	v_lshl_add_u64 v[2:3], s[12:13], 0, v[164:165]
	v_lshlrev_b64 v[2:3], 7, v[2:3]
	v_lshl_add_u64 v[4:5], v[180:181], 0, v[2:3]
	s_mov_b32 m0, s48
	v_lshl_add_u64 v[2:3], v[182:183], 0, v[2:3]
	global_load_lds_dwordx4 v[4:5], off
	s_mov_b32 m0, s49
	v_readlane_b32 s0, v254, 27
	global_load_lds_dwordx4 v[2:3], off
	v_add_u32_e32 v2, 0xfffff980, v6
	v_max_i32_e32 v164, 0, v2
	v_lshl_add_u64 v[2:3], s[12:13], 0, v[164:165]
	v_lshlrev_b64 v[2:3], 7, v[2:3]
	v_lshl_add_u64 v[4:5], v[180:181], 0, v[2:3]
	s_mov_b32 m0, s72
	v_and_b32_e32 v189, 31, v0
	global_load_lds_dwordx4 v[4:5], off
	v_lshl_add_u64 v[2:3], v[182:183], 0, v[2:3]
	s_mov_b32 m0, s0
	v_ashrrev_i32_e32 v1, 5, v0
	global_load_lds_dwordx4 v[2:3], off
	v_lshl_add_u32 v2, v189, 4, s11
	v_add_u32_e32 v4, 0x200, v2
	v_ashrrev_i32_e32 v5, 31, v4
	v_ashrrev_i32_e32 v3, 31, v2
	v_lshlrev_b32_e32 v184, 3, v1
	v_lshl_add_u64 v[4:5], s[12:13], 0, v[4:5]
	v_lshl_add_u64 v[2:3], s[12:13], 0, v[2:3]
	v_ashrrev_i32_e32 v185, 31, v184
	v_lshlrev_b64 v[4:5], 7, v[4:5]
	v_lshlrev_b64 v[2:3], 7, v[2:3]
	v_lshl_add_u64 v[4:5], s[92:93], 0, v[4:5]
	v_lshlrev_b64 v[6:7], 1, v[184:185]
	v_lshl_add_u64 v[2:3], s[92:93], 0, v[2:3]
	v_lshl_add_u64 v[4:5], v[4:5], 0, v[6:7]
	v_lshl_add_u64 v[2:3], v[2:3], 0, v[6:7]
	global_load_dwordx4 v[100:103], v[4:5], off offset:96
	global_load_dwordx4 v[104:107], v[4:5], off offset:64
	global_load_dwordx4 v[108:111], v[4:5], off offset:32
	global_load_dwordx4 v[112:115], v[4:5], off
	global_load_dwordx4 v[116:119], v[2:3], off offset:96
	global_load_dwordx4 v[120:123], v[2:3], off offset:64
	global_load_dwordx4 v[124:127], v[2:3], off offset:32
	global_load_dwordx4 v[128:131], v[2:3], off
	v_lshrrev_b32_e32 v2, 2, v0
	v_lshlrev_b32_e32 v193, 2, v1
	v_and_or_b32 v2, v2, 3, v193
	v_lshlrev_b32_e32 v3, 1, v0
	v_lshlrev_b32_e32 v2, 7, v2
	v_and_b32_e32 v3, 32, v3
	v_lshl_add_u64 v[186:187], s[92:93], 0, v[6:7]
	v_bitop3_b32 v6, v1, v0, 7 bitop3:0x78
	v_add_u32_e32 v7, 2, v1
	v_add_u32_e32 v8, 4, v1
	v_add_u32_e32 v1, 6, v1
	v_add3_u32 v2, s33, v2, v3
	v_lshlrev_b32_e32 v3, 3, v0
	v_cmp_gt_u32_e64 s[4:5], 32, v0
	v_bitop3_b32 v7, v7, v0, 7 bitop3:0x78
	v_bitop3_b32 v8, v8, v0, 7 bitop3:0x78
	v_bitop3_b32 v0, v1, v0, 7 bitop3:0x78
	v_and_b32_e32 v3, 24, v3
	v_lshl_add_u32 v4, v189, 7, s33
	v_or_b32_e32 v5, 0x80, v189
	v_lshlrev_b32_e32 v6, 4, v6
	v_lshlrev_b32_e32 v7, 4, v7
	v_lshlrev_b32_e32 v8, 4, v8
	v_lshlrev_b32_e32 v0, 4, v0
	v_add_u32_e32 v215, 32, v193
	v_add_u32_e32 v218, 64, v193
	v_add_u32_e32 v220, 0x60, v193
	s_mov_b32 s50, 1
	s_mov_b32 s20, 0
	v_sub_u32_e32 v214, v5, v193
	v_sub_u32_e32 v216, v5, v215
	v_subrev_u32_e32 v217, 32, v191
	v_sub_u32_e32 v219, v5, v218
	v_sub_u32_e32 v221, v5, v220
	v_add_u32_e32 v222, 32, v191
	v_add_u32_e32 v223, 0x80, v193
	v_sub_u32_e32 v224, v189, v193
	s_mov_b32 s56, 16
	v_mov_b32_e32 v230, 0
	v_add_u32_e32 v225, v4, v6
	v_add_u32_e32 v226, v4, v7
	v_add_u32_e32 v227, v4, v8
	v_add_u32_e32 v228, v4, v0
	v_add_u32_e32 v229, v2, v3
	s_lshl_b64 s[98:99], s[12:13], 7
	s_add_u32 s98, s98, s68
	s_addc_u32 s99, s99, s69
	s_add_u32 s100, s98, 0x17000000
	s_addc_u32 s101, s99, 0
	s_add_u32 s98, s98, 0x13000000
	s_addc_u32 s99, s99, 0
	v_and_b32_e32 v180, 0x70, v180
	v_and_b32_e32 v182, 0x70, v182
	s_branch .LBB0_61
.LBB0_60:
	s_xor_b64 s[2:3], s[2:3], -1
	s_add_i32 s50, s50, 1
	s_andn2_b64 vcc, exec, s[2:3]
	s_mov_b32 s11, s53
	s_mov_b32 s56, s52
	s_mov_b32 s20, s51
	v_mov_b32_e32 v230, v231
	s_mov_b32 s10, s54
	s_mov_b32 s16, s55
	s_mov_b64 s[12:13], s[0:1]
	s_mov_b64 s[98:99], s[30:31]
	s_mov_b64 s[100:101], s[34:35]
	s_cbranch_vccz .LBB0_118

; __device__ __forceinline__ bool att_params(int q, int nun, int G, int wave, AttJob& P) {
;     const int ui = q / 6, r = q - 6 * ui, br = r >> 1, jj = r & 1;
;     if (ui >= nun) return false;
;     int uid;
;     if (G == 256) { const int x = blockIdx.x & 7, sl = blockIdx.x >> 3; uid = ((x * 8 + (sl >> 2)) << 3) + (sl & 3) * 2 + ui; }
;     else { uid = blockIdx.x + ui * G; if (uid >= 512) return false; }
;     const int bh = uid >> 3, T0 = (uid & 7) * 1024;
;     const int d = br == 0 ? 16 : (br == 1 ? 4 : 1), pj = wave + 8 * jj;
;     const int p0 = d == 1 ? 64 * pj : (d == 4 ? 256 * (pj & 3) + (pj >> 2) : pj);
;     P.pos0 = T0 + p0; P.d = d; P.brmode = br; P.bar_after = (jj == 1 && br < 2) ? 1 : 0; P.b = bh >> 3; P.head = bh & 7; P.hb = (size_t)bh * SEQ;
.LBB0_75:
	s_lshl_b32 s1, s14, 10
	s_and_b32 s1, s1, 0x1c00
	s_ashr_i32 s0, s14, 3
	s_add_i32 s53, s6, s1
	s_cmp_lg_u32 s2, 0
	s_cselect_b64 s[2:3], -1, 0
	s_cmp_lt_i32 s51, 2
	s_cselect_b64 s[6:7], -1, 0
	s_and_b64 s[2:3], s[2:3], s[6:7]
	s_ashr_i32 s1, s0, 31
	v_cndmask_b32_e64 v231, 0, 1, s[2:3]
	s_ashr_i32 s54, s14, 6
	s_and_b32 s55, s0, 7
	s_lshl_b64 s[0:1], s[0:1], 13
	s_lshl_b64 s[30:31], s[0:1], 7
	s_add_u32 s30, s30, s68
	s_addc_u32 s31, s31, s69
	s_add_u32 s34, s30, 0x17000000
	s_addc_u32 s35, s31, 0
	s_add_u32 s30, s30, 0x13000000
	s_addc_u32 s31, s31, 0
	s_mov_b64 s[2:3], -1

; #define LAS __attribute__((address_space(3)))
; __device__ __forceinline__ void att_block(const bf16x8 (&kf)[4], const bf16x8 (&qf)[4], const bf16x8 (&va)[4], f32x16& o0, f32x16& o1, float& mrun, float& lrun, bool domask, int lo_, int hi_) {
;     ...
; #pragma unroll
;     for (int i = 0; i < 16; ++i) st[i] = 0.f;
; #pragma unroll
;     for (int kk = 0; kk < 4; ++kk) st = __builtin_amdgcn_mfma_f32_32x32x16_bf16(kf[kk], qf[kk], st, 0, 0, 0);
;     if (domask) {
;         asm volatile("" : "+v"(lo_), "+v"(hi_));
; #pragma unroll
;         for (int i = 0; i < 16; ++i) { const int ci = (i & 3) + 8 * (i >> 2); st[i] = ((ci - lo_) | (hi_ - ci)) < 0 ? -INFINITY : st[i]; }
;     }
;     float bmax = -INFINITY;
; #pragma unroll
;     for (int i = 0; i < 16; ++i) bmax = fmaxf(bmax, st[i]);
;     bmax = fmaxf(bmax, __shfl_xor(bmax, 32));
;     const float mnew = fmaxf(mrun, bmax);
;     float lsum = 0.f;
; #pragma unroll
;     for (int i = 0; i < 16; ++i) { st[i] = __builtin_amdgcn_exp2f(st[i] - mnew); lsum += st[i]; }
;     lsum += __shfl_xor(lsum, 32);
;     const float alpha = __builtin_amdgcn_exp2f(mrun - mnew);
;     lrun = lrun * alpha + lsum; mrun = mnew;
; #pragma unroll
; __device__ __forceinline__ void att_phase(unsigned char* ws, LAS unsigned char* lds, int lane, int wave, int G) {
;     ...
;             asm volatile("s_waitcnt vmcnt(0)" ::: "memory");
;             if (kb < 5) ATT_DMA_KV(P, kb + 1, sb ^ 1);
;             else if (hn) ATT_DMA_KV(N, 0, sb ^ 1);
;             bf16x8 kf[4], va[4];
; #pragma unroll
;             for (int kk = 0; kk < 4; ++kk) kf[kk] = *(LAS const bf16x8*)(kfb + sb * 4096 + (((2 * kk + h) ^ (qc & 7)) << 4));
;             LAS const unsigned char* trs = trb + 8192 + sb * 4096;
; #pragma unroll
;             for (int s = 0; s < 2; ++s) {
;                 const s16x4 lo0 = vtr(trs + (16 * s) * VP), hi0 = vtr(trs + (16 * s + 8) * VP);
;                 const s16x4 lo1 = vtr(trs + (16 * s) * VP + 64), hi1 = vtr(trs + (16 * s + 8) * VP + 64);
;                 va[2 * s] = (bf16x8){lo0[0], lo0[1], lo0[2], lo0[3], hi0[0], hi0[1], hi0[2], hi0[3]};
;                 va[2 * s + 1] = (bf16x8){lo1[0], lo1[1], lo1[2], lo1[3], hi1[0], hi1[1], hi1[2], hi1[3]};
;             }
;             if (kb <= 4) {
;                 att_block(kf, qfA, va, oA0, oA1, mA, lA, kb == 0 || kb == 4 || kminA > 32 * kb, mloA - 4 * h - 32 * kb, qc + 128 - 4 * h - 32 * kb);
.LBB0_80:
	v_add_u32_e32 v0, 0xffffffa0, v191
	v_mul_lo_u32 v0, s56, v0
	v_add_u32_e32 v4, s11, v0
	v_max_i32_e32 v164, 0, v4
	s_add_i32 s57, s33, 0x1000
	s_lshl_b32 s6, s56, 3
	s_waitcnt vmcnt(0)
	v_lshl_add_u32 v2, v164, 7, v180
	s_mov_b32 m0, s57
	s_add_i32 s7, s33, 0x3000
	v_add_u32_e32 v4, s6, v4
	global_load_lds_dwordx4 v2, s[98:99]
	v_lshl_add_u32 v0, v164, 7, v182
	s_mov_b32 m0, s7
	v_max_i32_e32 v164, 0, v4
	global_load_lds_dwordx4 v0, s[100:101]
	v_readlane_b32 s15, v254, 28
	v_lshl_add_u32 v2, v164, 7, v180
	s_mov_b32 m0, s15
	v_readlane_b32 s15, v254, 29
	v_add_u32_e32 v4, s6, v4
	global_load_lds_dwordx4 v2, s[98:99]
	v_lshl_add_u32 v0, v164, 7, v182
	s_mov_b32 m0, s15
	v_max_i32_e32 v164, 0, v4
	global_load_lds_dwordx4 v0, s[100:101]
	s_add_i32 s15, s33, 0x1800
	v_lshl_add_u32 v2, v164, 7, v180
	s_mov_b32 m0, s15
	s_add_i32 s17, s33, 0x3800
	v_add_u32_e32 v51, s6, v4
	global_load_lds_dwordx4 v2, s[98:99]
	v_lshl_add_u32 v0, v164, 7, v182
	s_mov_b32 m0, s17
	v_max_i32_e32 v164, 0, v51
	global_load_lds_dwordx4 v0, s[100:101]
	s_add_i32 s21, s33, 0x1c00
	v_lshl_add_u32 v2, v164, 7, v180
	s_mov_b32 m0, s21
	v_readlane_b32 s59, v254, 30
	global_load_lds_dwordx4 v2, s[98:99]
	v_lshl_add_u32 v0, v164, 7, v182
	s_mov_b32 m0, s59
	v_max_i32_e32 v199, s58, v189
	global_load_lds_dwordx4 v0, s[100:101]
	ds_read_b128 v[0:3], v225
	ds_read_b128 v[16:19], v226
	s_waitcnt vmcnt(0) lgkmcnt(0)
	v_mfma_f32_32x32x16_bf16 v[0:15], v[0:3], v[128:131], 0
	ds_read_b128 v[20:23], v228
	s_mov_b32 s59, 0xff800000
	v_mfma_f32_32x32x16_bf16 v[0:15], v[16:19], v[124:127], v[0:15]
	ds_read_b128 v[16:19], v227
	ds_read_b64_tr_b16 v[34:35], v229 offset:8192
	ds_read_b64_tr_b16 v[36:37], v229 offset:9216
	ds_read_b64_tr_b16 v[40:41], v229 offset:9280
	ds_read_b64_tr_b16 v[38:39], v229 offset:8256
	ds_read_b64_tr_b16 v[42:43], v229 offset:10240
	ds_read_b64_tr_b16 v[44:45], v229 offset:11264
	ds_read_b64_tr_b16 v[48:49], v229 offset:11328
	ds_read_b64_tr_b16 v[46:47], v229 offset:10304
	s_waitcnt lgkmcnt(8)
	v_mfma_f32_32x32x16_bf16 v[0:15], v[16:19], v[120:123], v[0:15]
	v_sub_u32_e32 v16, v199, v193
	v_mov_b32_e32 v17, v214
	s_waitcnt lgkmcnt(0)
	s_nop 0
	v_mfma_f32_32x32x16_bf16 v[0:15], v[20:23], v[116:119], v[0:15]
	s_nop 6
	v_cmp_ge_i32_e32 vcc, 0, v16
	v_cmp_ge_i32_e64 s[24:25], 1, v16
	v_cmp_ge_i32_e64 s[26:27], 2, v16
	v_cmp_ge_i32_e64 s[28:29], 3, v16
	s_nop 0
	v_cndmask_b32_e32 v0, v211, v0, vcc
	v_cmp_ge_i32_e32 vcc, 8, v16
	v_cndmask_b32_e64 v1, v211, v1, s[24:25]
	v_cmp_ge_i32_e64 s[24:25], 9, v16
	v_cndmask_b32_e64 v2, v211, v2, s[26:27]
	v_cmp_ge_i32_e64 s[26:27], 10, v16
	v_cndmask_b32_e64 v3, v211, v3, s[28:29]
	v_cmp_ge_i32_e64 s[28:29], 11, v16
	v_cndmask_b32_e32 v4, v211, v4, vcc
	v_cmp_ge_i32_e32 vcc, 16, v16
	v_cndmask_b32_e64 v5, v211, v5, s[24:25]
	v_cmp_ge_i32_e64 s[24:25], 17, v16
	v_cndmask_b32_e64 v6, v211, v6, s[26:27]
	v_cmp_ge_i32_e64 s[26:27], 18, v16
	v_cndmask_b32_e64 v7, v211, v7, s[28:29]
	v_cmp_ge_i32_e64 s[28:29], 19, v16
	v_cndmask_b32_e32 v8, v211, v8, vcc
	v_cmp_ge_i32_e32 vcc, 24, v16
	v_cndmask_b32_e64 v9, v211, v9, s[24:25]
	v_cmp_ge_i32_e64 s[24:25], 25, v16
	v_cndmask_b32_e64 v10, v211, v10, s[26:27]
	v_cmp_ge_i32_e64 s[26:27], 26, v16
	v_cndmask_b32_e64 v11, v211, v11, s[28:29]
	v_cmp_ge_i32_e64 s[28:29], 27, v16
	v_cndmask_b32_e32 v56, v211, v12, vcc
	v_cndmask_b32_e64 v57, v211, v13, s[24:25]
	v_cndmask_b32_e64 v58, v211, v14, s[26:27]
	v_cndmask_b32_e64 v59, v211, v15, s[28:29]
	s_nop 0
	s_nop 0
	v_max3_f32 v12, v0, s59, v1
	v_max3_f32 v12, v12, v2, v3
	v_max3_f32 v12, v12, v4, v5
	v_max3_f32 v12, v12, v6, v7
	v_max3_f32 v12, v12, v8, v9
	v_xor_b32_e32 v13, 32, v206
	v_max3_f32 v12, v12, v10, v11
	v_cmp_lt_i32_e32 vcc, v13, v208
	v_max3_f32 v12, v12, v56, v57
	v_max3_f32 v12, v12, v58, v59
	v_cndmask_b32_e32 v13, v206, v13, vcc
	v_lshlrev_b32_e32 v201, 2, v13
	ds_bpermute_b32 v13, v201, v12
	s_mov_b32 s59, 0xf149f2ca
	s_waitcnt lgkmcnt(0)
	v_max3_f32 v50, v12, v13, s59
	v_sub_f32_e32 v0, v0, v50
	v_exp_f32_e32 v16, v0
	v_sub_f32_e32 v0, v1, v50
	v_exp_f32_e32 v17, v0
	v_sub_f32_e32 v1, v2, v50
	v_exp_f32_e32 v18, v1
	v_sub_f32_e32 v1, v3, v50
	v_exp_f32_e32 v19, v1
	v_sub_f32_e32 v1, v4, v50
	v_add_f32_e32 v0, 0, v16
	v_exp_f32_e32 v20, v1
	v_sub_f32_e32 v1, v5, v50
	v_add_f32_e32 v0, v17, v0
	v_exp_f32_e32 v21, v1
	v_sub_f32_e32 v1, v6, v50
	v_add_f32_e32 v0, v18, v0
	v_exp_f32_e32 v22, v1
	v_sub_f32_e32 v1, v7, v50
	v_add_f32_e32 v0, v19, v0
	v_exp_f32_e32 v23, v1
	v_sub_f32_e32 v1, v8, v50
	v_add_f32_e32 v0, v20, v0
	v_exp_f32_e32 v60, v1
	v_sub_f32_e32 v1, v9, v50
	v_add_f32_e32 v0, v21, v0
	v_exp_f32_e32 v61, v1
	v_add_f32_e32 v0, v22, v0
	v_add_f32_e32 v0, v23, v0
	v_add_f32_e32 v0, v60, v0
	v_add_f32_e32 v62, v61, v0
	v_sub_f32_e32 v1, v10, v50
	v_cvt_pk_bf16_f32 v52, v16, v17
	v_sub_f32_e32 v16, v56, v50
	v_mov_b32_e32 v0, 0
	v_exp_f32_e32 v63, v1
	v_sub_f32_e32 v64, v11, v50
	v_cvt_pk_bf16_f32 v53, v18, v19
	v_cvt_pk_bf16_f32 v54, v20, v21
	v_cvt_pk_bf16_f32 v55, v22, v23
	v_exp_f32_e32 v56, v16
	v_sub_f32_e32 v16, v57, v50
	v_mfma_f32_32x32x16_bf16 v[18:33], v[34:37], v[52:55], 0
	v_exp_f32_e32 v57, v16
	v_sub_f32_e32 v34, v58, v50
	v_exp_f32_e32 v64, v64
	v_cvt_pk_bf16_f32 v36, v56, v57
	s_nop 1
	v_exp_f32_e32 v1, v34
	v_sub_f32_e32 v34, v59, v50
	v_mfma_f32_32x32x16_bf16 v[2:17], v[38:41], v[52:55], 0
	v_exp_f32_e32 v38, v34
	v_add_f32_e32 v39, v63, v62
	v_add_f32_e32 v39, v64, v39
	v_cvt_pk_bf16_f32 v34, v60, v61
	v_cvt_pk_bf16_f32 v35, v63, v64
	v_cvt_pk_bf16_f32 v37, v1, v38
	v_add_f32_e32 v39, v56, v39
	v_add_f32_e32 v39, v57, v39
	v_mfma_f32_32x32x16_bf16 v[18:33], v[42:45], v[34:37], v[18:33]
	v_add_f32_e32 v1, v1, v39
	v_add_f32_e32 v1, v38, v1
	ds_bpermute_b32 v232, v201, v1
	v_mfma_f32_32x32x16_bf16 v[2:17], v[46:49], v[34:37], v[2:17]
	v_add_u32_e32 v38, s6, v51
	v_max_i32_e32 v164, 0, v38
	s_mov_b32 m0, s33
	s_waitcnt vmcnt(0)
; #define LAS __attribute__((address_space(3)))
; __device__ __forceinline__ void att_block(const bf16x8 (&kf)[4], const bf16x8 (&qf)[4], const bf16x8 (&va)[4], f32x16& o0, f32x16& o1, float& mrun, float& lrun, bool domask, int lo_, int hi_) {
;     ...
; #pragma unroll
;     for (int i = 0; i < 16; ++i) st[i] = 0.f;
; #pragma unroll
;     for (int kk = 0; kk < 4; ++kk) st = __builtin_amdgcn_mfma_f32_32x32x16_bf16(kf[kk], qf[kk], st, 0, 0, 0);
;     if (domask) {
;         asm volatile("" : "+v"(lo_), "+v"(hi_));
; #pragma unroll
;         for (int i = 0; i < 16; ++i) { const int ci = (i & 3) + 8 * (i >> 2); st[i] = ((ci - lo_) | (hi_ - ci)) < 0 ? -INFINITY : st[i]; }
;     }
;     float bmax = -INFINITY;
; #pragma unroll
;     for (int i = 0; i < 16; ++i) bmax = fmaxf(bmax, st[i]);
;     bmax = fmaxf(bmax, __shfl_xor(bmax, 32));
;     const float mnew = fmaxf(mrun, bmax);
;     float lsum = 0.f;
; #pragma unroll
;     for (int i = 0; i < 16; ++i) { st[i] = __builtin_amdgcn_exp2f(st[i] - mnew); lsum += st[i]; }
;     lsum += __shfl_xor(lsum, 32);
;     const float alpha = __builtin_amdgcn_exp2f(mrun - mnew);
;     lrun = lrun * alpha + lsum; mrun = mnew;
; #pragma unroll
;     for (int i = 0; i < 16; ++i) { o0[i] *= alpha; o1[i] *= alpha; }
; #pragma unroll
; __device__ __forceinline__ void att_phase(unsigned char* ws, LAS unsigned char* lds, int lane, int wave, int G) {
;     ...
;             asm volatile("s_waitcnt vmcnt(0)" ::: "memory");
;             if (kb < 5) ATT_DMA_KV(P, kb + 1, sb ^ 1);
;             else if (hn) ATT_DMA_KV(N, 0, sb ^ 1);
;             bf16x8 kf[4], va[4];
; #pragma unroll
;             for (int kk = 0; kk < 4; ++kk) kf[kk] = *(LAS const bf16x8*)(kfb + sb * 4096 + (((2 * kk + h) ^ (qc & 7)) << 4));
;             LAS const unsigned char* trs = trb + 8192 + sb * 4096;
; #pragma unroll
;             for (int s = 0; s < 2; ++s) {
;                 const s16x4 lo0 = vtr(trs + (16 * s) * VP), hi0 = vtr(trs + (16 * s + 8) * VP);
;                 const s16x4 lo1 = vtr(trs + (16 * s) * VP + 64), hi1 = vtr(trs + (16 * s + 8) * VP + 64);
;                 va[2 * s] = (bf16x8){lo0[0], lo0[1], lo0[2], lo0[3], hi0[0], hi0[1], hi0[2], hi0[3]};
;                 va[2 * s + 1] = (bf16x8){lo1[0], lo1[1], lo1[2], lo1[3], hi1[0], hi1[1], hi1[2], hi1[3]};
;             }
	v_lshl_add_u32 v36, v164, 7, v180
	v_add_u32_e32 v38, s6, v38
	global_load_lds_dwordx4 v36, s[98:99]
	v_lshl_add_u32 v34, v164, 7, v182
	s_mov_b32 m0, s44
	v_max_i32_e32 v164, 0, v38
	global_load_lds_dwordx4 v34, s[100:101]
	v_lshl_add_u32 v36, v164, 7, v180
	s_mov_b32 m0, s66
	v_add_u32_e32 v38, s6, v38
	global_load_lds_dwordx4 v36, s[98:99]
	v_lshl_add_u32 v34, v164, 7, v182
	s_mov_b32 m0, s67
	v_max_i32_e32 v164, 0, v38
	global_load_lds_dwordx4 v34, s[100:101]
	v_lshl_add_u32 v36, v164, 7, v180
	s_mov_b32 m0, s48
	v_lshl_add_u32 v34, v164, 7, v182
	global_load_lds_dwordx4 v36, s[98:99]
	s_mov_b32 m0, s49
	v_readlane_b32 s59, v254, 27
	global_load_lds_dwordx4 v34, s[100:101]
	v_add_u32_e32 v34, s6, v38
	v_max_i32_e32 v164, 0, v34
	v_lshl_add_u32 v36, v164, 7, v180
	s_mov_b32 m0, s72
	v_lshl_add_u32 v34, v164, 7, v182
	global_load_lds_dwordx4 v36, s[98:99]
	s_mov_b32 m0, s59
	s_cmp_gt_i32 s58, 32
	global_load_lds_dwordx4 v34, s[100:101]
	ds_read_b128 v[68:71], v225 offset:4096
	ds_read_b128 v[64:67], v226 offset:4096
	s_waitcnt lgkmcnt(0)
	v_mfma_f32_32x32x16_bf16 v[34:49], v[68:71], v[128:131], 0
	ds_read_b128 v[60:63], v227 offset:4096
	ds_read_b128 v[56:59], v228 offset:4096
	s_waitcnt vmcnt(0)
	ds_read_b64_tr_b16 v[52:53], v229 offset:12288
	ds_read_b64_tr_b16 v[54:55], v229 offset:13312
	ds_read_b64_tr_b16 v[94:95], v229 offset:13376
	ds_read_b64_tr_b16 v[92:93], v229 offset:12352
	ds_read_b64_tr_b16 v[88:89], v229 offset:14336
	ds_read_b64_tr_b16 v[90:91], v229 offset:15360
	ds_read_b64_tr_b16 v[86:87], v229 offset:15424
	ds_read_b64_tr_b16 v[84:85], v229 offset:14400
	v_mfma_f32_32x32x16_bf16 v[34:49], v[64:67], v[124:127], v[34:49]
	s_waitcnt lgkmcnt(9)
	v_mfma_f32_32x32x16_bf16 v[34:49], v[60:63], v[120:123], v[34:49]
	s_waitcnt lgkmcnt(8)
	v_mfma_f32_32x32x16_bf16 v[34:49], v[56:59], v[116:119], v[34:49]
	s_cbranch_scc0 .LBB0_82
	v_sub_u32_e32 v51, v199, v215
	v_mov_b32_e32 v72, v216
	s_nop 0
	s_nop 1
	v_cmp_ge_i32_e32 vcc, 0, v51
	v_cmp_ge_i32_e64 s[24:25], 1, v51
	v_cmp_ge_i32_e64 s[26:27], 2, v51
	v_cmp_ge_i32_e64 s[28:29], 3, v51
	s_nop 1
	v_cndmask_b32_e32 v34, v211, v34, vcc
	v_cmp_ge_i32_e32 vcc, 8, v51
	v_cndmask_b32_e64 v35, v211, v35, s[24:25]
	v_cmp_ge_i32_e64 s[24:25], 9, v51
	v_cndmask_b32_e64 v36, v211, v36, s[26:27]
	v_cmp_ge_i32_e64 s[26:27], 10, v51
	v_cndmask_b32_e64 v37, v211, v37, s[28:29]
	v_cmp_ge_i32_e64 s[28:29], 11, v51
	v_cndmask_b32_e32 v38, v211, v38, vcc
	v_cmp_ge_i32_e32 vcc, 16, v51
	v_cndmask_b32_e64 v39, v211, v39, s[24:25]
	v_cmp_ge_i32_e64 s[24:25], 17, v51
	v_cndmask_b32_e64 v40, v211, v40, s[26:27]
	v_cmp_ge_i32_e64 s[26:27], 18, v51
	v_cndmask_b32_e64 v41, v211, v41, s[28:29]
	v_cmp_ge_i32_e64 s[28:29], 19, v51
	v_cndmask_b32_e32 v42, v211, v42, vcc
	v_cmp_ge_i32_e32 vcc, 24, v51
	v_cndmask_b32_e64 v43, v211, v43, s[24:25]
	v_cmp_ge_i32_e64 s[24:25], 25, v51
	v_cndmask_b32_e64 v44, v211, v44, s[26:27]
	v_cmp_ge_i32_e64 s[26:27], 26, v51
	v_cndmask_b32_e64 v45, v211, v45, s[28:29]
	v_cmp_ge_i32_e64 s[28:29], 27, v51
	v_cndmask_b32_e32 v46, v211, v46, vcc
	v_cndmask_b32_e64 v47, v211, v47, s[24:25]
	v_cndmask_b32_e64 v48, v211, v48, s[26:27]
	v_cndmask_b32_e64 v49, v211, v49, s[28:29]
	s_nop 0
	s_nop 1
.LBB0_82:
	s_mov_b32 s59, 0xff800000
	s_nop 9
	v_max3_f32 v51, v34, s59, v35
	v_max3_f32 v51, v51, v36, v37
	v_max3_f32 v51, v51, v38, v39
	v_max3_f32 v51, v51, v40, v41
	v_max3_f32 v51, v51, v42, v43
	v_max3_f32 v51, v51, v44, v45
	v_max3_f32 v51, v51, v46, v47
	v_max3_f32 v51, v51, v48, v49
	ds_bpermute_b32 v72, v201, v51
	v_max_i32_e32 v237, s14, v189
	s_mov_b32 s60, 0xff800000
	s_waitcnt lgkmcnt(0)
	v_max3_f32 v148, v50, v51, v72
	v_sub_f32_e32 v34, v34, v148
	v_exp_f32_e32 v72, v34
	v_sub_f32_e32 v35, v35, v148
	v_exp_f32_e32 v73, v35
	v_sub_f32_e32 v35, v36, v148
	v_exp_f32_e32 v74, v35
	v_sub_f32_e32 v35, v37, v148
	v_exp_f32_e32 v75, v35
	v_sub_f32_e32 v35, v38, v148
	v_add_f32_e32 v34, 0, v72
	v_exp_f32_e32 v76, v35
	v_sub_f32_e32 v35, v39, v148
	v_add_f32_e32 v34, v73, v34
	v_exp_f32_e32 v77, v35
	v_sub_f32_e32 v35, v40, v148
	v_add_f32_e32 v34, v74, v34
	v_exp_f32_e32 v78, v35
	v_sub_f32_e32 v35, v41, v148
	v_add_f32_e32 v34, v75, v34
	v_exp_f32_e32 v79, v35
	v_sub_f32_e32 v35, v42, v148
	v_add_f32_e32 v34, v76, v34
	v_exp_f32_e32 v80, v35
	v_sub_f32_e32 v35, v43, v148
	v_add_f32_e32 v34, v77, v34
	v_exp_f32_e32 v81, v35
	v_sub_f32_e32 v35, v44, v148
	v_add_f32_e32 v34, v78, v34
	v_exp_f32_e32 v82, v35
	v_sub_f32_e32 v35, v45, v148
	v_add_f32_e32 v34, v79, v34
	v_exp_f32_e32 v83, v35
	v_sub_f32_e32 v35, v46, v148
	v_add_f32_e32 v34, v80, v34
	v_exp_f32_e32 v96, v35
	v_sub_f32_e32 v35, v47, v148
	v_add_f32_e32 v34, v81, v34
	v_exp_f32_e32 v97, v35
	v_sub_f32_e32 v35, v48, v148
	v_add_f32_e32 v34, v82, v34
	v_exp_f32_e32 v98, v35
	v_sub_f32_e32 v35, v49, v148
	v_add_f32_e32 v34, v83, v34
	v_exp_f32_e32 v99, v35
	v_add_f32_e32 v34, v96, v34
	v_add_f32_e32 v34, v97, v34
	v_add_f32_e32 v34, v98, v34
	v_add_f32_e32 v235, v99, v34
	v_sub_f32_e32 v34, v50, v148
	v_exp_f32_e32 v188, v34
	ds_bpermute_b32 v236, v201, v235
	v_pk_mul_f32 v[34:35], v[32:33], v[188:189] op_sel_hi:[1,0]
	v_pk_mul_f32 v[32:33], v[30:31], v[188:189] op_sel_hi:[1,0]
	v_pk_mul_f32 v[30:31], v[28:29], v[188:189] op_sel_hi:[1,0]
	v_pk_mul_f32 v[28:29], v[26:27], v[188:189] op_sel_hi:[1,0]
	v_pk_mul_f32 v[26:27], v[24:25], v[188:189] op_sel_hi:[1,0]
	v_pk_mul_f32 v[24:25], v[22:23], v[188:189] op_sel_hi:[1,0]
	v_pk_mul_f32 v[22:23], v[20:21], v[188:189] op_sel_hi:[1,0]
	v_pk_mul_f32 v[20:21], v[18:19], v[188:189] op_sel_hi:[1,0]
	v_pk_mul_f32 v[50:51], v[16:17], v[188:189] op_sel_hi:[1,0]
	v_pk_mul_f32 v[48:49], v[14:15], v[188:189] op_sel_hi:[1,0]
	v_pk_mul_f32 v[46:47], v[12:13], v[188:189] op_sel_hi:[1,0]
	v_pk_mul_f32 v[44:45], v[10:11], v[188:189] op_sel_hi:[1,0]
	v_pk_mul_f32 v[42:43], v[8:9], v[188:189] op_sel_hi:[1,0]
	v_pk_mul_f32 v[40:41], v[6:7], v[188:189] op_sel_hi:[1,0]
	v_pk_mul_f32 v[38:39], v[4:5], v[188:189] op_sel_hi:[1,0]
	v_pk_mul_f32 v[36:37], v[2:3], v[188:189] op_sel_hi:[1,0]
	v_cvt_pk_bf16_f32 v2, v72, v73
	v_cvt_pk_bf16_f32 v3, v74, v75
	v_cvt_pk_bf16_f32 v4, v76, v77
	v_cvt_pk_bf16_f32 v5, v78, v79
	v_sub_u32_e32 v18, v237, v193
	v_mov_b32_e32 v19, v214
	v_mfma_f32_32x32x16_bf16 v[20:35], v[52:55], v[2:5], v[20:35]
	s_waitcnt lgkmcnt(0)
; __device__ __forceinline__ void att_block(const bf16x8 (&kf)[4], const bf16x8 (&qf)[4], const bf16x8 (&va)[4], f32x16& o0, f32x16& o1, float& mrun, float& lrun, bool domask, int lo_, int hi_) {
;     ...
; #pragma unroll
;     for (int i = 0; i < 16; ++i) st[i] = 0.f;
; #pragma unroll
;     for (int kk = 0; kk < 4; ++kk) st = __builtin_amdgcn_mfma_f32_32x32x16_bf16(kf[kk], qf[kk], st, 0, 0, 0);
;     if (domask) {
;         asm volatile("" : "+v"(lo_), "+v"(hi_));
; #pragma unroll
;         for (int i = 0; i < 16; ++i) { const int ci = (i & 3) + 8 * (i >> 2); st[i] = ((ci - lo_) | (hi_ - ci)) < 0 ? -INFINITY : st[i]; }
;     }
;     float bmax = -INFINITY;
; #pragma unroll
;     for (int i = 0; i < 16; ++i) bmax = fmaxf(bmax, st[i]);
;     bmax = fmaxf(bmax, __shfl_xor(bmax, 32));
;     const float mnew = fmaxf(mrun, bmax);
;     float lsum = 0.f;
; #pragma unroll
;     for (int i = 0; i < 16; ++i) { st[i] = __builtin_amdgcn_exp2f(st[i] - mnew); lsum += st[i]; }
;     lsum += __shfl_xor(lsum, 32);
;     const float alpha = __builtin_amdgcn_exp2f(mrun - mnew);
;     lrun = lrun * alpha + lsum; mrun = mnew;
; #pragma unroll
;     for (int i = 0; i < 16; ++i) { o0[i] *= alpha; o1[i] *= alpha; }
; #pragma unroll
;     for (int s = 0; s < 2; ++s) { v4u w; w.x = pk2(st[8 * s], st[8 * s + 1]); w.y = pk2(st[8 * s + 2], st[8 * s + 3]); w.z = pk2(st[8 * s + 4], st[8 * s + 5]); w.w = pk2(st[8 * s + 6], st[8 * s + 7]);
;         const bf16x8 pb = __builtin_bit_cast(bf16x8, w);
;         o0 = __builtin_amdgcn_mfma_f32_32x32x16_bf16(va[2 * s], pb, o0, 0, 0, 0);
;         o1 = __builtin_amdgcn_mfma_f32_32x32x16_bf16(va[2 * s + 1], pb, o1, 0, 0, 0); }
; __device__ __forceinline__ void att_phase(unsigned char* ws, LAS unsigned char* lds, int lane, int wave, int G) {
;     ...
;             asm volatile("s_waitcnt vmcnt(0)" ::: "memory");
;             if (kb < 5) ATT_DMA_KV(P, kb + 1, sb ^ 1);
;             else if (hn) ATT_DMA_KV(N, 0, sb ^ 1);
;             bf16x8 kf[4], va[4];
; #pragma unroll
;             for (int kk = 0; kk < 4; ++kk) kf[kk] = *(LAS const bf16x8*)(kfb + sb * 4096 + (((2 * kk + h) ^ (qc & 7)) << 4));
;             LAS const unsigned char* trs = trb + 8192 + sb * 4096;
; #pragma unroll
;             for (int s = 0; s < 2; ++s) {
;                 const s16x4 lo0 = vtr(trs + (16 * s) * VP), hi0 = vtr(trs + (16 * s + 8) * VP);
	v_mfma_f32_32x32x16_bf16 v[36:51], v[92:95], v[2:5], v[36:51]
	v_cvt_pk_bf16_f32 v2, v80, v81
	v_cvt_pk_bf16_f32 v3, v82, v83
	v_cvt_pk_bf16_f32 v4, v96, v97
	v_cvt_pk_bf16_f32 v5, v98, v99
	s_nop 1
	v_mfma_f32_32x32x16_bf16 v[20:35], v[88:91], v[2:5], v[20:35]
	v_mfma_f32_32x32x16_bf16 v[36:51], v[84:87], v[2:5], v[36:51]
	v_mfma_f32_32x32x16_bf16 v[2:17], v[68:71], v[112:115], 0
	v_mfma_f32_32x32x16_bf16 v[2:17], v[64:67], v[108:111], v[2:17]
	v_mfma_f32_32x32x16_bf16 v[2:17], v[60:63], v[104:107], v[2:17]
	v_mfma_f32_32x32x16_bf16 v[2:17], v[56:59], v[100:103], v[2:17]
	s_nop 4
	v_cmp_ge_i32_e32 vcc, 0, v18
	v_cmp_ge_i32_e64 s[24:25], 1, v18
	v_cmp_ge_i32_e64 s[26:27], 2, v18
	v_cmp_ge_i32_e64 s[28:29], 3, v18
	s_nop 2
	v_cndmask_b32_e32 v2, v211, v2, vcc
	v_cmp_ge_i32_e32 vcc, 8, v18
	v_cndmask_b32_e64 v3, v211, v3, s[24:25]
	v_cmp_ge_i32_e64 s[24:25], 9, v18
	v_cndmask_b32_e64 v4, v211, v4, s[26:27]
	v_cmp_ge_i32_e64 s[26:27], 10, v18
	v_cndmask_b32_e64 v5, v211, v5, s[28:29]
	v_cmp_ge_i32_e64 s[28:29], 11, v18
	v_cndmask_b32_e32 v6, v211, v6, vcc
	v_cmp_ge_i32_e32 vcc, 16, v18
	v_cndmask_b32_e64 v7, v211, v7, s[24:25]
	v_cmp_ge_i32_e64 s[24:25], 17, v18
	v_cndmask_b32_e64 v8, v211, v8, s[26:27]
	v_cmp_ge_i32_e64 s[26:27], 18, v18
	v_cndmask_b32_e64 v9, v211, v9, s[28:29]
	v_cmp_ge_i32_e64 s[28:29], 19, v18
	v_cndmask_b32_e32 v10, v211, v10, vcc
	v_cmp_ge_i32_e32 vcc, 24, v18
	v_cndmask_b32_e64 v11, v211, v11, s[24:25]
	v_cmp_ge_i32_e64 s[24:25], 25, v18
	v_cndmask_b32_e64 v12, v211, v12, s[26:27]
	v_cmp_ge_i32_e64 s[26:27], 26, v18
	v_cndmask_b32_e64 v13, v211, v13, s[28:29]
	v_cmp_ge_i32_e64 s[28:29], 27, v18
	v_cndmask_b32_e32 v14, v211, v14, vcc
	v_cndmask_b32_e64 v15, v211, v15, s[24:25]
	v_cndmask_b32_e64 v16, v211, v16, s[26:27]
	v_cndmask_b32_e64 v17, v211, v17, s[28:29]
	s_nop 0
	v_max3_f32 v18, v2, s59, v3
	v_max3_f32 v18, v18, v4, v5
	v_max3_f32 v18, v18, v6, v7
	v_max3_f32 v18, v18, v8, v9
	v_max3_f32 v18, v18, v10, v11
	v_max3_f32 v18, v18, v12, v13
	v_max3_f32 v18, v18, v14, v15
	v_max3_f32 v18, v18, v16, v17
	ds_bpermute_b32 v19, v201, v18
	s_mov_b32 s59, 0xf149f2ca
	s_waitcnt lgkmcnt(0)
	v_max3_f32 v150, v18, v19, s59
	v_sub_f32_e32 v2, v2, v150
	v_exp_f32_e32 v18, v2
	v_sub_f32_e32 v3, v3, v150
	v_exp_f32_e32 v19, v3
	v_sub_f32_e32 v3, v4, v150
	v_exp_f32_e32 v56, v3
	v_sub_f32_e32 v3, v5, v150
	v_exp_f32_e32 v57, v3
	v_sub_f32_e32 v3, v6, v150
	v_add_f32_e32 v2, 0, v18
	v_exp_f32_e32 v58, v3
	v_sub_f32_e32 v3, v7, v150
	v_add_f32_e32 v2, v19, v2
	v_exp_f32_e32 v59, v3
	v_sub_f32_e32 v3, v8, v150
	v_add_f32_e32 v2, v56, v2
	v_exp_f32_e32 v60, v3
	v_sub_f32_e32 v3, v9, v150
	v_add_f32_e32 v2, v57, v2
	v_exp_f32_e32 v61, v3
	v_sub_f32_e32 v3, v10, v150
	v_add_f32_e32 v2, v58, v2
	v_exp_f32_e32 v132, v3
	v_sub_f32_e32 v3, v11, v150
	v_add_f32_e32 v2, v59, v2
	v_exp_f32_e32 v133, v3
	v_sub_f32_e32 v3, v12, v150
	v_add_f32_e32 v2, v60, v2
	v_exp_f32_e32 v134, v3
	v_sub_f32_e32 v3, v13, v150
	v_add_f32_e32 v2, v61, v2
	v_exp_f32_e32 v135, v3
	v_sub_f32_e32 v3, v14, v150
	v_add_f32_e32 v2, v132, v2
	v_exp_f32_e32 v136, v3
	v_sub_f32_e32 v3, v15, v150
	v_add_f32_e32 v2, v133, v2
	v_exp_f32_e32 v137, v3
	v_sub_f32_e32 v3, v16, v150
	v_add_f32_e32 v2, v134, v2
	v_exp_f32_e32 v138, v3
	v_sub_f32_e32 v3, v17, v150
	v_add_f32_e32 v2, v135, v2
	v_exp_f32_e32 v139, v3
	v_add_f32_e32 v2, v136, v2
	v_add_f32_e32 v2, v137, v2
	v_add_f32_e32 v2, v138, v2
	v_add_f32_e32 v233, v139, v2
	v_cvt_pk_bf16_f32 v96, v18, v19
	v_cvt_pk_bf16_f32 v97, v56, v57
	v_cvt_pk_bf16_f32 v98, v58, v59
	v_mov_b32_e32 v2, 0
	v_cvt_pk_bf16_f32 v99, v60, v61
	ds_bpermute_b32 v234, v201, v233
	s_nop 0
	v_mfma_f32_32x32x16_bf16 v[68:83], v[52:55], v[96:99], 0
	v_cvt_pk_bf16_f32 v4, v132, v133
	v_cvt_pk_bf16_f32 v5, v134, v135
	v_mfma_f32_32x32x16_bf16 v[52:67], v[92:95], v[96:99], 0
	v_cvt_pk_bf16_f32 v6, v136, v137
	v_cvt_pk_bf16_f32 v7, v138, v139
	s_nop 1
	v_mfma_f32_32x32x16_bf16 v[68:83], v[88:91], v[4:7], v[68:83]
	v_mfma_f32_32x32x16_bf16 v[52:67], v[84:87], v[4:7], v[52:67]
	v_mul_lo_u32 v3, s56, v217
	v_add_u32_e32 v3, s11, v3
	v_max_i32_e32 v164, 0, v3
	s_mov_b32 m0, s57
	s_waitcnt vmcnt(0)
	v_lshl_add_u32 v6, v164, 7, v180
	v_add_u32_e32 v3, s6, v3
	global_load_lds_dwordx4 v6, s[98:99]
	v_lshl_add_u32 v4, v164, 7, v182
	s_mov_b32 m0, s7
	v_max_i32_e32 v164, 0, v3
	global_load_lds_dwordx4 v4, s[100:101]
	v_readlane_b32 s59, v254, 28
	v_lshl_add_u32 v6, v164, 7, v180
	s_mov_b32 m0, s59
	v_readlane_b32 s59, v254, 29
	v_add_u32_e32 v3, s6, v3
	global_load_lds_dwordx4 v6, s[98:99]
	v_lshl_add_u32 v4, v164, 7, v182
	s_mov_b32 m0, s59
	v_max_i32_e32 v164, 0, v3
	global_load_lds_dwordx4 v4, s[100:101]
	v_lshl_add_u32 v6, v164, 7, v180
	s_mov_b32 m0, s15
	v_add_u32_e32 v3, s6, v3
	global_load_lds_dwordx4 v6, s[98:99]
	v_lshl_add_u32 v4, v164, 7, v182
	s_mov_b32 m0, s17
	v_max_i32_e32 v164, 0, v3
	global_load_lds_dwordx4 v4, s[100:101]
	v_lshl_add_u32 v6, v164, 7, v180
	s_mov_b32 m0, s21
	v_readlane_b32 s59, v254, 30
	global_load_lds_dwordx4 v6, s[98:99]
	v_lshl_add_u32 v4, v164, 7, v182
	s_mov_b32 m0, s59
	s_cmpk_lt_i32 s58, 0x41
	global_load_lds_dwordx4 v4, s[100:101]
	ds_read_b128 v[144:147], v225
	ds_read_b128 v[140:143], v226
	s_waitcnt lgkmcnt(0)
	v_mfma_f32_32x32x16_bf16 v[4:19], v[144:147], v[128:131], 0
	ds_read_b128 v[136:139], v227
	ds_read_b128 v[132:135], v228
	s_waitcnt vmcnt(0)
	ds_read_b64_tr_b16 v[96:97], v229 offset:8192
	ds_read_b64_tr_b16 v[98:99], v229 offset:9216
	ds_read_b64_tr_b16 v[94:95], v229 offset:9280
	ds_read_b64_tr_b16 v[92:93], v229 offset:8256
	ds_read_b64_tr_b16 v[88:89], v229 offset:10240
	ds_read_b64_tr_b16 v[90:91], v229 offset:11264
	ds_read_b64_tr_b16 v[86:87], v229 offset:11328
	ds_read_b64_tr_b16 v[84:85], v229 offset:10304
	v_mfma_f32_32x32x16_bf16 v[4:19], v[140:143], v[124:127], v[4:19]
	s_waitcnt lgkmcnt(9)
	v_mfma_f32_32x32x16_bf16 v[4:19], v[136:139], v[120:123], v[4:19]
	s_waitcnt lgkmcnt(8)
	v_mfma_f32_32x32x16_bf16 v[4:19], v[132:135], v[116:119], v[4:19]
	s_cbranch_scc1 .LBB0_84
; __device__ __forceinline__ unsigned pk2(float lo, float hi) { return pg8::cvt_pk_bf16(lo, hi); }
; __device__ __forceinline__ void att_block(const bf16x8 (&kf)[4], const bf16x8 (&qf)[4], const bf16x8 (&va)[4], f32x16& o0, f32x16& o1, float& mrun, float& lrun, bool domask, int lo_, int hi_) {
;     ...
; #pragma unroll
;     for (int i = 0; i < 16; ++i) st[i] = 0.f;
; #pragma unroll
;     for (int kk = 0; kk < 4; ++kk) st = __builtin_amdgcn_mfma_f32_32x32x16_bf16(kf[kk], qf[kk], st, 0, 0, 0);
;     if (domask) {
;         asm volatile("" : "+v"(lo_), "+v"(hi_));
; #pragma unroll
;         for (int i = 0; i < 16; ++i) { const int ci = (i & 3) + 8 * (i >> 2); st[i] = ((ci - lo_) | (hi_ - ci)) < 0 ? -INFINITY : st[i]; }
;     }
;     float bmax = -INFINITY;
; #pragma unroll
;     for (int i = 0; i < 16; ++i) bmax = fmaxf(bmax, st[i]);
;     bmax = fmaxf(bmax, __shfl_xor(bmax, 32));
;     const float mnew = fmaxf(mrun, bmax);
;     float lsum = 0.f;
; #pragma unroll
;     for (int i = 0; i < 16; ++i) { st[i] = __builtin_amdgcn_exp2f(st[i] - mnew); lsum += st[i]; }
;     lsum += __shfl_xor(lsum, 32);
;     const float alpha = __builtin_amdgcn_exp2f(mrun - mnew);
;     lrun = lrun * alpha + lsum; mrun = mnew;
; #pragma unroll
;     for (int i = 0; i < 16; ++i) { o0[i] *= alpha; o1[i] *= alpha; }
; #pragma unroll
;     for (int s = 0; s < 2; ++s) { v4u w; w.x = pk2(st[8 * s], st[8 * s + 1]); w.y = pk2(st[8 * s + 2], st[8 * s + 3]); w.z = pk2(st[8 * s + 4], st[8 * s + 5]); w.w = pk2(st[8 * s + 6], st[8 * s + 7]);
;         const bf16x8 pb = __builtin_bit_cast(bf16x8, w);
;         o0 = __builtin_amdgcn_mfma_f32_32x32x16_bf16(va[2 * s], pb, o0, 0, 0, 0);
;         o1 = __builtin_amdgcn_mfma_f32_32x32x16_bf16(va[2 * s + 1], pb, o1, 0, 0, 0); }
; __device__ __forceinline__ void att_phase(unsigned char* ws, LAS unsigned char* lds, int lane, int wave, int G) {
;     ...
;                 att_block(kf, qfA, va, oA0, oA1, mA, lA, kb == 0 || kb == 4 || kminA > 32 * kb, mloA - 4 * h - 32 * kb, qc + 128 - 4 * h - 32 * kb);
;                 if (kb == 4 && hn) ATT_LOAD_Q(qfA, N, 0);
;             }
;             if (kb >= 1) {
;                 att_block(kf, qfB, va, oB0, oB1, mB, lB, kb == 1 || kb == 5 || kminB > 32 * (kb - 1), mloB - 4 * h - 32 * (kb - 1), qc + 128 - 4 * h - 32 * (kb - 1));
	v_sub_u32_e32 v3, v199, v218
	v_mov_b32_e32 v149, v219
	s_nop 0
	s_nop 1
	v_cmp_ge_i32_e32 vcc, 0, v3
	v_cmp_ge_i32_e64 s[24:25], 1, v3
	v_cmp_ge_i32_e64 s[26:27], 2, v3
	v_cmp_ge_i32_e64 s[28:29], 3, v3
	s_nop 1
	v_cndmask_b32_e32 v4, v211, v4, vcc
	v_cmp_ge_i32_e32 vcc, 8, v3
	v_cndmask_b32_e64 v5, v211, v5, s[24:25]
	v_cmp_ge_i32_e64 s[24:25], 9, v3
	v_cndmask_b32_e64 v6, v211, v6, s[26:27]
	v_cmp_ge_i32_e64 s[26:27], 10, v3
	v_cndmask_b32_e64 v7, v211, v7, s[28:29]
	v_cmp_ge_i32_e64 s[28:29], 11, v3
	v_cndmask_b32_e32 v8, v211, v8, vcc
	v_cmp_ge_i32_e32 vcc, 16, v3
	v_cndmask_b32_e64 v9, v211, v9, s[24:25]
	v_cmp_ge_i32_e64 s[24:25], 17, v3
	v_cndmask_b32_e64 v10, v211, v10, s[26:27]
	v_cmp_ge_i32_e64 s[26:27], 18, v3
	v_cndmask_b32_e64 v11, v211, v11, s[28:29]
	v_cmp_ge_i32_e64 s[28:29], 19, v3
	v_cndmask_b32_e32 v12, v211, v12, vcc
	v_cmp_ge_i32_e32 vcc, 24, v3
	v_cndmask_b32_e64 v13, v211, v13, s[24:25]
	v_cmp_ge_i32_e64 s[24:25], 25, v3
	v_cndmask_b32_e64 v14, v211, v14, s[26:27]
	v_cmp_ge_i32_e64 s[26:27], 26, v3
	v_cndmask_b32_e64 v15, v211, v15, s[28:29]
	v_cmp_ge_i32_e64 s[28:29], 27, v3
	v_cndmask_b32_e32 v16, v211, v16, vcc
	v_cndmask_b32_e64 v17, v211, v17, s[24:25]
	v_cndmask_b32_e64 v18, v211, v18, s[26:27]
	v_cndmask_b32_e64 v19, v211, v19, s[28:29]
	s_nop 0
	s_nop 1
.LBB0_84:
	s_nop 10
	v_max3_f32 v3, v4, s60, v5
	v_max3_f32 v3, v3, v6, v7
	v_max3_f32 v3, v3, v8, v9
	v_max3_f32 v3, v3, v10, v11
	v_max3_f32 v3, v3, v12, v13
	v_max3_f32 v3, v3, v14, v15
	v_max3_f32 v3, v3, v16, v17
	v_max3_f32 v3, v3, v18, v19
	ds_bpermute_b32 v149, v201, v3
	s_cmp_lt_i32 s14, 33
	s_waitcnt lgkmcnt(0)
	v_max3_f32 v149, v148, v3, v149
	v_sub_f32_e32 v3, v4, v149
	v_exp_f32_e32 v3, v3
	v_sub_f32_e32 v5, v5, v149
	v_exp_f32_e32 v151, v5
	v_sub_f32_e32 v5, v6, v149
	v_exp_f32_e32 v152, v5
	v_sub_f32_e32 v5, v7, v149
	v_exp_f32_e32 v153, v5
	v_sub_f32_e32 v5, v8, v149
	v_add_f32_e32 v4, 0, v3
	v_exp_f32_e32 v154, v5
	v_sub_f32_e32 v5, v9, v149
	v_add_f32_e32 v4, v151, v4
	v_exp_f32_e32 v155, v5
	v_sub_f32_e32 v5, v10, v149
	v_add_f32_e32 v4, v152, v4
	v_exp_f32_e32 v156, v5
	v_sub_f32_e32 v5, v11, v149
	v_add_f32_e32 v4, v153, v4
	v_exp_f32_e32 v157, v5
	v_sub_f32_e32 v5, v12, v149
	v_add_f32_e32 v4, v154, v4
	v_exp_f32_e32 v158, v5
	v_sub_f32_e32 v5, v13, v149
	v_add_f32_e32 v4, v155, v4
	v_exp_f32_e32 v159, v5
	v_sub_f32_e32 v5, v14, v149
	v_add_f32_e32 v4, v156, v4
	v_exp_f32_e32 v160, v5
	v_sub_f32_e32 v5, v15, v149
	v_add_f32_e32 v4, v157, v4
	v_exp_f32_e32 v161, v5
	v_sub_f32_e32 v5, v16, v149
	v_add_f32_e32 v4, v158, v4
	v_exp_f32_e32 v162, v5
	v_sub_f32_e32 v5, v17, v149
	v_add_f32_e32 v4, v159, v4
	v_exp_f32_e32 v163, v5
	v_sub_f32_e32 v5, v18, v149
	v_add_f32_e32 v4, v160, v4
	v_exp_f32_e32 v164, v5
	v_sub_f32_e32 v5, v19, v149
	v_add_f32_e32 v4, v161, v4
	v_exp_f32_e32 v166, v5
	v_add_f32_e32 v4, v162, v4
	v_add_f32_e32 v4, v163, v4
	v_add_f32_e32 v4, v164, v4
	v_add_f32_e32 v239, v166, v4
	v_sub_f32_e32 v4, v148, v149
	v_exp_f32_e32 v192, v4
	ds_bpermute_b32 v240, v201, v239
	v_pk_mul_f32 v[18:19], v[34:35], v[192:193] op_sel_hi:[1,0]
	v_pk_mul_f32 v[16:17], v[32:33], v[192:193] op_sel_hi:[1,0]
	v_pk_mul_f32 v[14:15], v[30:31], v[192:193] op_sel_hi:[1,0]
	v_pk_mul_f32 v[12:13], v[28:29], v[192:193] op_sel_hi:[1,0]
	v_pk_mul_f32 v[10:11], v[26:27], v[192:193] op_sel_hi:[1,0]
	v_pk_mul_f32 v[8:9], v[24:25], v[192:193] op_sel_hi:[1,0]
	v_pk_mul_f32 v[6:7], v[22:23], v[192:193] op_sel_hi:[1,0]
	v_pk_mul_f32 v[4:5], v[20:21], v[192:193] op_sel_hi:[1,0]
	v_pk_mul_f32 v[34:35], v[50:51], v[192:193] op_sel_hi:[1,0]
	v_pk_mul_f32 v[32:33], v[48:49], v[192:193] op_sel_hi:[1,0]
	v_pk_mul_f32 v[30:31], v[46:47], v[192:193] op_sel_hi:[1,0]
	v_pk_mul_f32 v[28:29], v[44:45], v[192:193] op_sel_hi:[1,0]
	v_pk_mul_f32 v[26:27], v[42:43], v[192:193] op_sel_hi:[1,0]
	v_pk_mul_f32 v[24:25], v[40:41], v[192:193] op_sel_hi:[1,0]
	v_pk_mul_f32 v[22:23], v[38:39], v[192:193] op_sel_hi:[1,0]
	v_pk_mul_f32 v[20:21], v[36:37], v[192:193] op_sel_hi:[1,0]
	v_cvt_pk_bf16_f32 v36, v3, v151
	v_cvt_pk_bf16_f32 v37, v152, v153
	v_cvt_pk_bf16_f32 v38, v154, v155
	v_cvt_pk_bf16_f32 v39, v156, v157
	s_nop 1
	v_mfma_f32_32x32x16_bf16 v[4:19], v[96:99], v[36:39], v[4:19]
	v_mfma_f32_32x32x16_bf16 v[20:35], v[92:95], v[36:39], v[20:35]
	v_cvt_pk_bf16_f32 v36, v158, v159
	v_cvt_pk_bf16_f32 v37, v160, v161
	v_cvt_pk_bf16_f32 v38, v162, v163
	v_cvt_pk_bf16_f32 v39, v164, v166
	s_nop 1
	v_mfma_f32_32x32x16_bf16 v[4:19], v[88:91], v[36:39], v[4:19]
	v_mfma_f32_32x32x16_bf16 v[20:35], v[84:87], v[36:39], v[20:35]
	v_mfma_f32_32x32x16_bf16 v[36:51], v[144:147], v[112:115], 0
	v_mfma_f32_32x32x16_bf16 v[36:51], v[140:143], v[108:111], v[36:51]
	v_mfma_f32_32x32x16_bf16 v[36:51], v[136:139], v[104:107], v[36:51]
	v_mfma_f32_32x32x16_bf16 v[36:51], v[132:135], v[100:103], v[36:51]
	s_cbranch_scc1 .LBB0_86
	v_sub_u32_e32 v3, v237, v215
	v_mov_b32_e32 v132, v216
	s_nop 0
	s_nop 1
	v_cmp_ge_i32_e32 vcc, 0, v3
	v_cmp_ge_i32_e64 s[24:25], 1, v3
	v_cmp_ge_i32_e64 s[26:27], 2, v3
	v_cmp_ge_i32_e64 s[28:29], 3, v3
	s_nop 1
	v_cndmask_b32_e32 v36, v211, v36, vcc
	v_cmp_ge_i32_e32 vcc, 8, v3
	v_cndmask_b32_e64 v37, v211, v37, s[24:25]
	v_cmp_ge_i32_e64 s[24:25], 9, v3
	v_cndmask_b32_e64 v38, v211, v38, s[26:27]
	v_cmp_ge_i32_e64 s[26:27], 10, v3
	v_cndmask_b32_e64 v39, v211, v39, s[28:29]
	v_cmp_ge_i32_e64 s[28:29], 11, v3
	v_cndmask_b32_e32 v40, v211, v40, vcc
	v_cmp_ge_i32_e32 vcc, 16, v3
	v_cndmask_b32_e64 v41, v211, v41, s[24:25]
	v_cmp_ge_i32_e64 s[24:25], 17, v3
	v_cndmask_b32_e64 v42, v211, v42, s[26:27]
	v_cmp_ge_i32_e64 s[26:27], 18, v3
	v_cndmask_b32_e64 v43, v211, v43, s[28:29]
	v_cmp_ge_i32_e64 s[28:29], 19, v3
	v_cndmask_b32_e32 v44, v211, v44, vcc
	v_cmp_ge_i32_e32 vcc, 24, v3
	v_cndmask_b32_e64 v45, v211, v45, s[24:25]
	v_cmp_ge_i32_e64 s[24:25], 25, v3
	v_cndmask_b32_e64 v46, v211, v46, s[26:27]
	v_cmp_ge_i32_e64 s[26:27], 26, v3
	v_cndmask_b32_e64 v47, v211, v47, s[28:29]
	v_cmp_ge_i32_e64 s[28:29], 27, v3
	v_cndmask_b32_e32 v48, v211, v48, vcc
	v_cndmask_b32_e64 v49, v211, v49, s[24:25]
	v_cndmask_b32_e64 v50, v211, v50, s[26:27]
	v_cndmask_b32_e64 v51, v211, v51, s[28:29]
	s_nop 0
	s_nop 1
; __device__ __forceinline__ void att_block(const bf16x8 (&kf)[4], const bf16x8 (&qf)[4], const bf16x8 (&va)[4], f32x16& o0, f32x16& o1, float& mrun, float& lrun, bool domask, int lo_, int hi_) {
;     ...
; #pragma unroll
;     for (int i = 0; i < 16; ++i) st[i] = 0.f;
; #pragma unroll
;     for (int kk = 0; kk < 4; ++kk) st = __builtin_amdgcn_mfma_f32_32x32x16_bf16(kf[kk], qf[kk], st, 0, 0, 0);
;     if (domask) {
;         asm volatile("" : "+v"(lo_), "+v"(hi_));
; #pragma unroll
;         for (int i = 0; i < 16; ++i) { const int ci = (i & 3) + 8 * (i >> 2); st[i] = ((ci - lo_) | (hi_ - ci)) < 0 ? -INFINITY : st[i]; }
;     }
;     float bmax = -INFINITY;
; #pragma unroll
;     for (int i = 0; i < 16; ++i) bmax = fmaxf(bmax, st[i]);
;     bmax = fmaxf(bmax, __shfl_xor(bmax, 32));
;     const float mnew = fmaxf(mrun, bmax);
;     float lsum = 0.f;
; #pragma unroll
;     for (int i = 0; i < 16; ++i) { st[i] = __builtin_amdgcn_exp2f(st[i] - mnew); lsum += st[i]; }
;     lsum += __shfl_xor(lsum, 32);
;     const float alpha = __builtin_amdgcn_exp2f(mrun - mnew);
;     lrun = lrun * alpha + lsum; mrun = mnew;
; #pragma unroll
;     for (int i = 0; i < 16; ++i) { o0[i] *= alpha; o1[i] *= alpha; }
; #pragma unroll
;     for (int s = 0; s < 2; ++s) { v4u w; w.x = pk2(st[8 * s], st[8 * s + 1]); w.y = pk2(st[8 * s + 2], st[8 * s + 3]); w.z = pk2(st[8 * s + 4], st[8 * s + 5]); w.w = pk2(st[8 * s + 6], st[8 * s + 7]);
;         const bf16x8 pb = __builtin_bit_cast(bf16x8, w);
;         o0 = __builtin_amdgcn_mfma_f32_32x32x16_bf16(va[2 * s], pb, o0, 0, 0, 0);
;         o1 = __builtin_amdgcn_mfma_f32_32x32x16_bf16(va[2 * s + 1], pb, o1, 0, 0, 0); }
; __device__ __forceinline__ void att_phase(unsigned char* ws, LAS unsigned char* lds, int lane, int wave, int G) {
;     ...
;             asm volatile("s_waitcnt vmcnt(0)" ::: "memory");
;             if (kb < 5) ATT_DMA_KV(P, kb + 1, sb ^ 1);
;             else if (hn) ATT_DMA_KV(N, 0, sb ^ 1);
;             bf16x8 kf[4], va[4];
; #pragma unroll
;             for (int kk = 0; kk < 4; ++kk) kf[kk] = *(LAS const bf16x8*)(kfb + sb * 4096 + (((2 * kk + h) ^ (qc & 7)) << 4));
;             LAS const unsigned char* trs = trb + 8192 + sb * 4096;
; #pragma unroll
;             for (int s = 0; s < 2; ++s) {
;                 const s16x4 lo0 = vtr(trs + (16 * s) * VP), hi0 = vtr(trs + (16 * s + 8) * VP);
.LBB0_86:
	s_nop 10
	v_max3_f32 v3, v36, s60, v37
	v_max3_f32 v3, v3, v38, v39
	v_max3_f32 v3, v3, v40, v41
	v_max3_f32 v3, v3, v42, v43
	v_max3_f32 v3, v3, v44, v45
	v_max3_f32 v3, v3, v46, v47
	v_max3_f32 v3, v3, v48, v49
	v_max3_f32 v3, v3, v50, v51
	ds_bpermute_b32 v132, v201, v3
	s_waitcnt lgkmcnt(0)
	s_waitcnt lgkmcnt(0)
	v_max3_f32 v148, v150, v3, v132
	v_sub_f32_e32 v3, v36, v148
	v_sub_f32_e32 v36, v37, v148
	v_exp_f32_e32 v133, v36
	v_sub_f32_e32 v36, v38, v148
	v_exp_f32_e32 v134, v36
	v_sub_f32_e32 v36, v39, v148
	v_exp_f32_e32 v135, v36
	v_sub_f32_e32 v36, v40, v148
	v_exp_f32_e32 v136, v36
	v_sub_f32_e32 v36, v41, v148
	v_exp_f32_e32 v137, v36
	v_sub_f32_e32 v36, v42, v148
	v_exp_f32_e32 v138, v36
	v_sub_f32_e32 v36, v43, v148
	v_exp_f32_e32 v139, v36
	v_sub_f32_e32 v36, v44, v148
	v_exp_f32_e32 v140, v36
	v_sub_f32_e32 v36, v45, v148
	v_exp_f32_e32 v141, v36
	v_sub_f32_e32 v36, v46, v148
	v_exp_f32_e32 v142, v36
	v_sub_f32_e32 v36, v47, v148
	v_exp_f32_e32 v143, v36
	v_sub_f32_e32 v36, v48, v148
	v_exp_f32_e32 v132, v3
	v_exp_f32_e32 v144, v36
	v_sub_f32_e32 v36, v49, v148
	v_exp_f32_e32 v145, v36
	v_sub_f32_e32 v36, v50, v148
	v_exp_f32_e32 v146, v36
	v_sub_f32_e32 v36, v51, v148
	v_exp_f32_e32 v147, v36
	v_sub_f32_e32 v36, v150, v148
	v_add_f32_e32 v3, 0, v132
	v_exp_f32_e32 v190, v36
	v_add_f32_e32 v3, v133, v3
	v_add_f32_e32 v3, v134, v3
	v_add_f32_e32 v3, v135, v3
	v_add_f32_e32 v3, v136, v3
	v_pk_mul_f32 v[50:51], v[82:83], v[190:191] op_sel_hi:[1,0]
	v_pk_mul_f32 v[48:49], v[80:81], v[190:191] op_sel_hi:[1,0]
	v_pk_mul_f32 v[46:47], v[78:79], v[190:191] op_sel_hi:[1,0]
	v_pk_mul_f32 v[44:45], v[76:77], v[190:191] op_sel_hi:[1,0]
	v_pk_mul_f32 v[42:43], v[74:75], v[190:191] op_sel_hi:[1,0]
	v_pk_mul_f32 v[40:41], v[72:73], v[190:191] op_sel_hi:[1,0]
	v_pk_mul_f32 v[38:39], v[70:71], v[190:191] op_sel_hi:[1,0]
	v_pk_mul_f32 v[36:37], v[68:69], v[190:191] op_sel_hi:[1,0]
	v_pk_mul_f32 v[66:67], v[66:67], v[190:191] op_sel_hi:[1,0]
	v_pk_mul_f32 v[64:65], v[64:65], v[190:191] op_sel_hi:[1,0]
	v_pk_mul_f32 v[62:63], v[62:63], v[190:191] op_sel_hi:[1,0]
	v_pk_mul_f32 v[60:61], v[60:61], v[190:191] op_sel_hi:[1,0]
	v_pk_mul_f32 v[58:59], v[58:59], v[190:191] op_sel_hi:[1,0]
	v_pk_mul_f32 v[56:57], v[56:57], v[190:191] op_sel_hi:[1,0]
	v_pk_mul_f32 v[54:55], v[54:55], v[190:191] op_sel_hi:[1,0]
	v_pk_mul_f32 v[52:53], v[52:53], v[190:191] op_sel_hi:[1,0]
	v_cvt_pk_bf16_f32 v68, v132, v133
	v_cvt_pk_bf16_f32 v69, v134, v135
	v_cvt_pk_bf16_f32 v70, v136, v137
	v_cvt_pk_bf16_f32 v71, v138, v139
	v_add_f32_e32 v3, v137, v3
	v_add_f32_e32 v3, v138, v3
	v_mfma_f32_32x32x16_bf16 v[36:51], v[96:99], v[68:71], v[36:51]
	v_add_f32_e32 v3, v139, v3
	v_add_f32_e32 v3, v140, v3
	v_add_f32_e32 v3, v141, v3
	v_add_f32_e32 v3, v142, v3
	v_add_f32_e32 v3, v143, v3
	v_add_f32_e32 v3, v144, v3
	v_add_f32_e32 v3, v145, v3
	v_mfma_f32_32x32x16_bf16 v[52:67], v[92:95], v[68:71], v[52:67]
	v_cvt_pk_bf16_f32 v68, v140, v141
	v_cvt_pk_bf16_f32 v69, v142, v143
	v_cvt_pk_bf16_f32 v70, v144, v145
	v_cvt_pk_bf16_f32 v71, v146, v147
	v_add_f32_e32 v3, v146, v3
	v_add_f32_e32 v3, v147, v3
	ds_bpermute_b32 v238, v201, v3
	v_mfma_f32_32x32x16_bf16 v[36:51], v[88:91], v[68:71], v[36:51]
	v_mfma_f32_32x32x16_bf16 v[52:67], v[84:87], v[68:71], v[52:67]
	v_mul_lo_u32 v68, s56, v191
	v_add_u32_e32 v72, s11, v68
	v_max_i32_e32 v164, 0, v72
	s_mov_b32 m0, s33
	s_waitcnt vmcnt(0)
	v_lshl_add_u32 v70, v164, 7, v180
	v_add_u32_e32 v72, s6, v72
	global_load_lds_dwordx4 v70, s[98:99]
	v_lshl_add_u32 v68, v164, 7, v182
	s_mov_b32 m0, s44
	v_max_i32_e32 v164, 0, v72
	global_load_lds_dwordx4 v68, s[100:101]
	v_lshl_add_u32 v70, v164, 7, v180
	s_mov_b32 m0, s66
	v_add_u32_e32 v72, s6, v72
	global_load_lds_dwordx4 v70, s[98:99]
	v_lshl_add_u32 v68, v164, 7, v182
	s_mov_b32 m0, s67
	v_max_i32_e32 v164, 0, v72
	global_load_lds_dwordx4 v68, s[100:101]
	v_lshl_add_u32 v70, v164, 7, v180
	s_mov_b32 m0, s48
	v_lshl_add_u32 v68, v164, 7, v182
	global_load_lds_dwordx4 v70, s[98:99]
	s_mov_b32 m0, s49
	v_readlane_b32 s59, v254, 27
	global_load_lds_dwordx4 v68, s[100:101]
	v_add_u32_e32 v68, s6, v72
	v_max_i32_e32 v164, 0, v68
	v_lshl_add_u32 v70, v164, 7, v180
	s_mov_b32 m0, s72
	v_lshl_add_u32 v68, v164, 7, v182
	global_load_lds_dwordx4 v70, s[98:99]
	s_mov_b32 m0, s59
	s_cmpk_lt_i32 s58, 0x61
	global_load_lds_dwordx4 v68, s[100:101]
	ds_read_b128 v[96:99], v225 offset:4096
	ds_read_b128 v[92:95], v226 offset:4096
	s_waitcnt lgkmcnt(0)
	v_mfma_f32_32x32x16_bf16 v[68:83], v[96:99], v[128:131], 0
	ds_read_b128 v[88:91], v227 offset:4096
	ds_read_b128 v[84:87], v228 offset:4096
	s_waitcnt vmcnt(0)
	ds_read_b64_tr_b16 v[144:145], v229 offset:12288
	ds_read_b64_tr_b16 v[146:147], v229 offset:13312
	ds_read_b64_tr_b16 v[142:143], v229 offset:13376
	ds_read_b64_tr_b16 v[140:141], v229 offset:12352
	ds_read_b64_tr_b16 v[136:137], v229 offset:14336
	ds_read_b64_tr_b16 v[138:139], v229 offset:15360
	ds_read_b64_tr_b16 v[134:135], v229 offset:15424
	ds_read_b64_tr_b16 v[132:133], v229 offset:14400
	v_mfma_f32_32x32x16_bf16 v[68:83], v[92:95], v[124:127], v[68:83]
	s_waitcnt lgkmcnt(9)
	v_mfma_f32_32x32x16_bf16 v[68:83], v[88:91], v[120:123], v[68:83]
	s_waitcnt lgkmcnt(8)
	v_mfma_f32_32x32x16_bf16 v[68:83], v[84:87], v[116:119], v[68:83]
	s_cbranch_scc1 .LBB0_88
	v_sub_u32_e32 v150, v199, v220
	v_mov_b32_e32 v151, v221
	s_nop 0
	s_nop 1
	v_cmp_ge_i32_e32 vcc, 0, v150
	v_cmp_ge_i32_e64 s[24:25], 1, v150
	v_cmp_ge_i32_e64 s[26:27], 2, v150
	v_cmp_ge_i32_e64 s[28:29], 3, v150
	s_nop 1
	v_cndmask_b32_e32 v68, v211, v68, vcc
	v_cmp_ge_i32_e32 vcc, 8, v150
	v_cndmask_b32_e64 v69, v211, v69, s[24:25]
	v_cmp_ge_i32_e64 s[24:25], 9, v150
	v_cndmask_b32_e64 v70, v211, v70, s[26:27]
	v_cmp_ge_i32_e64 s[26:27], 10, v150
	v_cndmask_b32_e64 v71, v211, v71, s[28:29]
	v_cmp_ge_i32_e64 s[28:29], 11, v150
	v_cndmask_b32_e32 v72, v211, v72, vcc
	v_cmp_ge_i32_e32 vcc, 16, v150
	v_cndmask_b32_e64 v73, v211, v73, s[24:25]
	v_cmp_ge_i32_e64 s[24:25], 17, v150
	v_cndmask_b32_e64 v74, v211, v74, s[26:27]
	v_cmp_ge_i32_e64 s[26:27], 18, v150
	v_cndmask_b32_e64 v75, v211, v75, s[28:29]
	v_cmp_ge_i32_e64 s[28:29], 19, v150
	v_cndmask_b32_e32 v76, v211, v76, vcc
	v_cmp_ge_i32_e32 vcc, 24, v150
	v_cndmask_b32_e64 v77, v211, v77, s[24:25]
	v_cmp_ge_i32_e64 s[24:25], 25, v150
	v_cndmask_b32_e64 v78, v211, v78, s[26:27]
	v_cmp_ge_i32_e64 s[26:27], 26, v150
	v_cndmask_b32_e64 v79, v211, v79, s[28:29]
	v_cmp_ge_i32_e64 s[28:29], 27, v150
	v_cndmask_b32_e32 v80, v211, v80, vcc
	v_cndmask_b32_e64 v81, v211, v81, s[24:25]
	v_cndmask_b32_e64 v82, v211, v82, s[26:27]
	v_cndmask_b32_e64 v83, v211, v83, s[28:29]
	s_nop 0
	s_nop 1
; __device__ __forceinline__ unsigned pk2(float lo, float hi) { return pg8::cvt_pk_bf16(lo, hi); }
; __device__ __forceinline__ void att_block(const bf16x8 (&kf)[4], const bf16x8 (&qf)[4], const bf16x8 (&va)[4], f32x16& o0, f32x16& o1, float& mrun, float& lrun, bool domask, int lo_, int hi_) {
;     ...
; #pragma unroll
;     for (int i = 0; i < 16; ++i) st[i] = 0.f;
; #pragma unroll
;     for (int kk = 0; kk < 4; ++kk) st = __builtin_amdgcn_mfma_f32_32x32x16_bf16(kf[kk], qf[kk], st, 0, 0, 0);
;     if (domask) {
;         asm volatile("" : "+v"(lo_), "+v"(hi_));
; #pragma unroll
;         for (int i = 0; i < 16; ++i) { const int ci = (i & 3) + 8 * (i >> 2); st[i] = ((ci - lo_) | (hi_ - ci)) < 0 ? -INFINITY : st[i]; }
;     }
;     float bmax = -INFINITY;
; #pragma unroll
;     for (int i = 0; i < 16; ++i) bmax = fmaxf(bmax, st[i]);
;     bmax = fmaxf(bmax, __shfl_xor(bmax, 32));
;     const float mnew = fmaxf(mrun, bmax);
;     float lsum = 0.f;
; #pragma unroll
;     for (int i = 0; i < 16; ++i) { st[i] = __builtin_amdgcn_exp2f(st[i] - mnew); lsum += st[i]; }
;     lsum += __shfl_xor(lsum, 32);
;     const float alpha = __builtin_amdgcn_exp2f(mrun - mnew);
;     lrun = lrun * alpha + lsum; mrun = mnew;
; #pragma unroll
;     for (int i = 0; i < 16; ++i) { o0[i] *= alpha; o1[i] *= alpha; }
; #pragma unroll
;     for (int s = 0; s < 2; ++s) { v4u w; w.x = pk2(st[8 * s], st[8 * s + 1]); w.y = pk2(st[8 * s + 2], st[8 * s + 3]); w.z = pk2(st[8 * s + 4], st[8 * s + 5]); w.w = pk2(st[8 * s + 6], st[8 * s + 7]);
;         const bf16x8 pb = __builtin_bit_cast(bf16x8, w);
;         o0 = __builtin_amdgcn_mfma_f32_32x32x16_bf16(va[2 * s], pb, o0, 0, 0, 0);
;         o1 = __builtin_amdgcn_mfma_f32_32x32x16_bf16(va[2 * s + 1], pb, o1, 0, 0, 0); }
; __device__ __forceinline__ void att_phase(unsigned char* ws, LAS unsigned char* lds, int lane, int wave, int G) {
;     ...
;             if (kb >= 1) {
;                 att_block(kf, qfB, va, oB0, oB1, mB, lB, kb == 1 || kb == 5 || kminB > 32 * (kb - 1), mloB - 4 * h - 32 * (kb - 1), qc + 128 - 4 * h - 32 * (kb - 1));
.LBB0_88:
	s_nop 10
	v_max3_f32 v150, v68, s60, v69
	v_max3_f32 v150, v150, v70, v71
	v_max3_f32 v150, v150, v72, v73
	v_max3_f32 v150, v150, v74, v75
	v_max3_f32 v150, v150, v76, v77
	v_max3_f32 v150, v150, v78, v79
	v_max3_f32 v150, v150, v80, v81
	v_max3_f32 v150, v150, v82, v83
	ds_bpermute_b32 v151, v201, v150
	s_cmpk_lt_i32 s14, 0x41
	s_waitcnt lgkmcnt(0)
	v_max3_f32 v202, v149, v150, v151
	v_sub_f32_e32 v68, v68, v202
	v_exp_f32_e32 v68, v68
	v_sub_f32_e32 v69, v69, v202
	v_exp_f32_e32 v69, v69
	v_sub_f32_e32 v70, v70, v202
	v_exp_f32_e32 v70, v70
	v_sub_f32_e32 v71, v71, v202
	v_exp_f32_e32 v71, v71
	v_sub_f32_e32 v72, v72, v202
	v_add_f32_e32 v150, 0, v68
	v_exp_f32_e32 v72, v72
	v_sub_f32_e32 v73, v73, v202
	v_add_f32_e32 v150, v69, v150
	v_exp_f32_e32 v73, v73
	v_sub_f32_e32 v74, v74, v202
	v_sub_f32_e32 v75, v75, v202
	v_sub_f32_e32 v149, v149, v202
	v_add_f32_e32 v150, v70, v150
	v_exp_f32_e32 v74, v74
	v_exp_f32_e32 v75, v75
	v_exp_f32_e32 v196, v149
	v_add_f32_e32 v150, v71, v150
	v_sub_f32_e32 v76, v76, v202
	v_add_f32_e32 v150, v72, v150
	v_exp_f32_e32 v76, v76
	v_sub_f32_e32 v77, v77, v202
	v_add_f32_e32 v150, v73, v150
	v_exp_f32_e32 v77, v77
	v_sub_f32_e32 v78, v78, v202
	v_add_f32_e32 v150, v74, v150
	v_exp_f32_e32 v78, v78
	v_sub_f32_e32 v79, v79, v202
	v_pk_mul_f32 v[18:19], v[18:19], v[196:197] op_sel_hi:[1,0]
	v_pk_mul_f32 v[16:17], v[16:17], v[196:197] op_sel_hi:[1,0]
	v_pk_mul_f32 v[14:15], v[14:15], v[196:197] op_sel_hi:[1,0]
	v_pk_mul_f32 v[12:13], v[12:13], v[196:197] op_sel_hi:[1,0]
	v_pk_mul_f32 v[10:11], v[10:11], v[196:197] op_sel_hi:[1,0]
	v_pk_mul_f32 v[8:9], v[8:9], v[196:197] op_sel_hi:[1,0]
	v_pk_mul_f32 v[6:7], v[6:7], v[196:197] op_sel_hi:[1,0]
	v_pk_mul_f32 v[4:5], v[4:5], v[196:197] op_sel_hi:[1,0]
	v_pk_mul_f32 v[34:35], v[34:35], v[196:197] op_sel_hi:[1,0]
	v_pk_mul_f32 v[32:33], v[32:33], v[196:197] op_sel_hi:[1,0]
	v_pk_mul_f32 v[30:31], v[30:31], v[196:197] op_sel_hi:[1,0]
	v_pk_mul_f32 v[28:29], v[28:29], v[196:197] op_sel_hi:[1,0]
	v_pk_mul_f32 v[26:27], v[26:27], v[196:197] op_sel_hi:[1,0]
	v_pk_mul_f32 v[24:25], v[24:25], v[196:197] op_sel_hi:[1,0]
	v_pk_mul_f32 v[22:23], v[22:23], v[196:197] op_sel_hi:[1,0]
	v_pk_mul_f32 v[20:21], v[20:21], v[196:197] op_sel_hi:[1,0]
	v_cvt_pk_bf16_f32 v68, v68, v69
	v_cvt_pk_bf16_f32 v69, v70, v71
	v_cvt_pk_bf16_f32 v70, v72, v73
	v_cvt_pk_bf16_f32 v71, v74, v75
	v_add_f32_e32 v150, v75, v150
	v_exp_f32_e32 v79, v79
	v_sub_f32_e32 v80, v80, v202
	v_mfma_f32_32x32x16_bf16 v[4:19], v[144:147], v[68:71], v[4:19]
	v_add_f32_e32 v150, v76, v150
	v_exp_f32_e32 v80, v80
	v_sub_f32_e32 v81, v81, v202
	v_add_f32_e32 v150, v77, v150
	v_exp_f32_e32 v81, v81
	v_sub_f32_e32 v82, v82, v202
	v_sub_f32_e32 v83, v83, v202
	v_mfma_f32_32x32x16_bf16 v[20:35], v[140:143], v[68:71], v[20:35]
	v_add_f32_e32 v150, v78, v150
	v_exp_f32_e32 v82, v82
	v_exp_f32_e32 v83, v83
	v_add_f32_e32 v150, v79, v150
	v_add_f32_e32 v150, v80, v150
	v_add_f32_e32 v150, v81, v150
	v_add_f32_e32 v150, v82, v150
	v_cvt_pk_bf16_f32 v68, v76, v77
	v_cvt_pk_bf16_f32 v69, v78, v79
	v_cvt_pk_bf16_f32 v70, v80, v81
	v_cvt_pk_bf16_f32 v71, v82, v83
	v_add_f32_e32 v243, v83, v150
	ds_bpermute_b32 v244, v201, v243
	v_mfma_f32_32x32x16_bf16 v[4:19], v[136:139], v[68:71], v[4:19]
	v_mfma_f32_32x32x16_bf16 v[20:35], v[132:135], v[68:71], v[20:35]
	v_mfma_f32_32x32x16_bf16 v[68:83], v[96:99], v[112:115], 0
	v_mfma_f32_32x32x16_bf16 v[68:83], v[92:95], v[108:111], v[68:83]
	v_mfma_f32_32x32x16_bf16 v[68:83], v[88:91], v[104:107], v[68:83]
	v_mfma_f32_32x32x16_bf16 v[68:83], v[84:87], v[100:103], v[68:83]
	s_cbranch_scc1 .LBB0_90
	v_sub_u32_e32 v84, v237, v218
	v_mov_b32_e32 v85, v219
	s_nop 0
	s_nop 1
	v_cmp_ge_i32_e32 vcc, 0, v84
	v_cmp_ge_i32_e64 s[24:25], 1, v84
	v_cmp_ge_i32_e64 s[26:27], 2, v84
	v_cmp_ge_i32_e64 s[28:29], 3, v84
	s_nop 1
	v_cndmask_b32_e32 v68, v211, v68, vcc
	v_cmp_ge_i32_e32 vcc, 8, v84
	v_cndmask_b32_e64 v69, v211, v69, s[24:25]
	v_cmp_ge_i32_e64 s[24:25], 9, v84
	v_cndmask_b32_e64 v70, v211, v70, s[26:27]
	v_cmp_ge_i32_e64 s[26:27], 10, v84
	v_cndmask_b32_e64 v71, v211, v71, s[28:29]
	v_cmp_ge_i32_e64 s[28:29], 11, v84
	v_cndmask_b32_e32 v72, v211, v72, vcc
	v_cmp_ge_i32_e32 vcc, 16, v84
	v_cndmask_b32_e64 v73, v211, v73, s[24:25]
	v_cmp_ge_i32_e64 s[24:25], 17, v84
	v_cndmask_b32_e64 v74, v211, v74, s[26:27]
	v_cmp_ge_i32_e64 s[26:27], 18, v84
	v_cndmask_b32_e64 v75, v211, v75, s[28:29]
	v_cmp_ge_i32_e64 s[28:29], 19, v84
	v_cndmask_b32_e32 v76, v211, v76, vcc
	v_cmp_ge_i32_e32 vcc, 24, v84
	v_cndmask_b32_e64 v77, v211, v77, s[24:25]
	v_cmp_ge_i32_e64 s[24:25], 25, v84
	v_cndmask_b32_e64 v78, v211, v78, s[26:27]
	v_cmp_ge_i32_e64 s[26:27], 26, v84
	v_cndmask_b32_e64 v79, v211, v79, s[28:29]
	v_cmp_ge_i32_e64 s[28:29], 27, v84
	v_cndmask_b32_e32 v80, v211, v80, vcc
	v_cndmask_b32_e64 v81, v211, v81, s[24:25]
	v_cndmask_b32_e64 v82, v211, v82, s[26:27]
	v_cndmask_b32_e64 v83, v211, v83, s[28:29]
	s_nop 0
	s_nop 1
; __device__ __forceinline__ void att_block(const bf16x8 (&kf)[4], const bf16x8 (&qf)[4], const bf16x8 (&va)[4], f32x16& o0, f32x16& o1, float& mrun, float& lrun, bool domask, int lo_, int hi_) {
;     ...
; #pragma unroll
;     for (int i = 0; i < 16; ++i) st[i] = 0.f;
; #pragma unroll
;     for (int kk = 0; kk < 4; ++kk) st = __builtin_amdgcn_mfma_f32_32x32x16_bf16(kf[kk], qf[kk], st, 0, 0, 0);
;     if (domask) {
;         asm volatile("" : "+v"(lo_), "+v"(hi_));
; #pragma unroll
;         for (int i = 0; i < 16; ++i) { const int ci = (i & 3) + 8 * (i >> 2); st[i] = ((ci - lo_) | (hi_ - ci)) < 0 ? -INFINITY : st[i]; }
;     }
;     float bmax = -INFINITY;
; #pragma unroll
;     for (int i = 0; i < 16; ++i) bmax = fmaxf(bmax, st[i]);
;     bmax = fmaxf(bmax, __shfl_xor(bmax, 32));
;     const float mnew = fmaxf(mrun, bmax);
;     float lsum = 0.f;
; #pragma unroll
;     for (int i = 0; i < 16; ++i) { st[i] = __builtin_amdgcn_exp2f(st[i] - mnew); lsum += st[i]; }
;     lsum += __shfl_xor(lsum, 32);
;     const float alpha = __builtin_amdgcn_exp2f(mrun - mnew);
;     lrun = lrun * alpha + lsum; mrun = mnew;
; #pragma unroll
;     for (int i = 0; i < 16; ++i) { o0[i] *= alpha; o1[i] *= alpha; }
; #pragma unroll
;     for (int s = 0; s < 2; ++s) { v4u w; w.x = pk2(st[8 * s], st[8 * s + 1]); w.y = pk2(st[8 * s + 2], st[8 * s + 3]); w.z = pk2(st[8 * s + 4], st[8 * s + 5]); w.w = pk2(st[8 * s + 6], st[8 * s + 7]);
;         const bf16x8 pb = __builtin_bit_cast(bf16x8, w);
;         o0 = __builtin_amdgcn_mfma_f32_32x32x16_bf16(va[2 * s], pb, o0, 0, 0, 0);
;         o1 = __builtin_amdgcn_mfma_f32_32x32x16_bf16(va[2 * s + 1], pb, o1, 0, 0, 0); }
; __device__ __forceinline__ void att_phase(unsigned char* ws, LAS unsigned char* lds, int lane, int wave, int G) {
;     ...
;             asm volatile("s_waitcnt vmcnt(0)" ::: "memory");
;             if (kb < 5) ATT_DMA_KV(P, kb + 1, sb ^ 1);
;             else if (hn) ATT_DMA_KV(N, 0, sb ^ 1);
;             bf16x8 kf[4], va[4];
; #pragma unroll
;             for (int kk = 0; kk < 4; ++kk) kf[kk] = *(LAS const bf16x8*)(kfb + sb * 4096 + (((2 * kk + h) ^ (qc & 7)) << 4));
;             LAS const unsigned char* trs = trb + 8192 + sb * 4096;
; #pragma unroll
;             for (int s = 0; s < 2; ++s) {
;                 const s16x4 lo0 = vtr(trs + (16 * s) * VP), hi0 = vtr(trs + (16 * s + 8) * VP);
.LBB0_90:
	v_mul_lo_u32 v84, s52, v189
	s_mov_b32 s58, 0xff800000
	v_add_u32_e32 v198, s53, v84
	s_nop 7
	v_max3_f32 v84, v68, s58, v69
	v_max3_f32 v84, v84, v70, v71
	v_max3_f32 v84, v84, v72, v73
	v_max3_f32 v84, v84, v74, v75
	v_max3_f32 v84, v84, v76, v77
	v_max3_f32 v84, v84, v78, v79
	v_max3_f32 v84, v84, v80, v81
	v_max3_f32 v84, v84, v82, v83
	ds_bpermute_b32 v85, v201, v84
	s_waitcnt lgkmcnt(0)
	s_waitcnt lgkmcnt(0)
	v_max3_f32 v245, v148, v84, v85
	v_sub_f32_e32 v68, v68, v245
	v_exp_f32_e32 v149, v68
	v_sub_f32_e32 v69, v69, v245
	v_exp_f32_e32 v150, v69
	v_sub_f32_e32 v69, v70, v245
	v_exp_f32_e32 v151, v69
	v_sub_f32_e32 v69, v71, v245
	v_exp_f32_e32 v152, v69
	v_sub_f32_e32 v69, v72, v245
	v_add_f32_e32 v68, 0, v149
	v_exp_f32_e32 v153, v69
	v_sub_f32_e32 v69, v73, v245
	v_add_f32_e32 v68, v150, v68
	v_exp_f32_e32 v154, v69
	v_sub_f32_e32 v69, v74, v245
	v_add_f32_e32 v68, v151, v68
	v_exp_f32_e32 v155, v69
	v_sub_f32_e32 v69, v75, v245
	v_add_f32_e32 v68, v152, v68
	v_exp_f32_e32 v156, v69
	v_sub_f32_e32 v69, v76, v245
	v_add_f32_e32 v68, v153, v68
	v_exp_f32_e32 v157, v69
	v_sub_f32_e32 v69, v77, v245
	v_add_f32_e32 v68, v154, v68
	v_exp_f32_e32 v158, v69
	v_sub_f32_e32 v69, v78, v245
	v_add_f32_e32 v68, v155, v68
	v_exp_f32_e32 v159, v69
	v_sub_f32_e32 v69, v79, v245
	v_add_f32_e32 v68, v156, v68
	v_exp_f32_e32 v160, v69
	v_sub_f32_e32 v69, v80, v245
	v_add_f32_e32 v68, v157, v68
	v_exp_f32_e32 v161, v69
	v_sub_f32_e32 v69, v81, v245
	v_add_f32_e32 v68, v158, v68
	v_exp_f32_e32 v162, v69
	v_sub_f32_e32 v69, v82, v245
	v_add_f32_e32 v68, v159, v68
	v_exp_f32_e32 v163, v69
	v_sub_f32_e32 v69, v83, v245
	v_add_f32_e32 v68, v160, v68
	v_exp_f32_e32 v164, v69
	v_add_f32_e32 v68, v161, v68
	v_add_f32_e32 v68, v162, v68
	v_add_f32_e32 v68, v163, v68
	v_add_f32_e32 v241, v164, v68
	v_sub_f32_e32 v68, v148, v245
	v_exp_f32_e32 v194, v68
	ds_bpermute_b32 v242, v201, v241
	v_pk_mul_f32 v[82:83], v[50:51], v[194:195] op_sel_hi:[1,0]
	v_pk_mul_f32 v[80:81], v[48:49], v[194:195] op_sel_hi:[1,0]
	v_pk_mul_f32 v[78:79], v[46:47], v[194:195] op_sel_hi:[1,0]
	v_pk_mul_f32 v[76:77], v[44:45], v[194:195] op_sel_hi:[1,0]
	v_pk_mul_f32 v[74:75], v[42:43], v[194:195] op_sel_hi:[1,0]
	v_pk_mul_f32 v[72:73], v[40:41], v[194:195] op_sel_hi:[1,0]
	v_pk_mul_f32 v[70:71], v[38:39], v[194:195] op_sel_hi:[1,0]
	v_pk_mul_f32 v[68:69], v[36:37], v[194:195] op_sel_hi:[1,0]
	v_pk_mul_f32 v[98:99], v[66:67], v[194:195] op_sel_hi:[1,0]
	v_pk_mul_f32 v[96:97], v[64:65], v[194:195] op_sel_hi:[1,0]
	v_pk_mul_f32 v[94:95], v[62:63], v[194:195] op_sel_hi:[1,0]
	v_pk_mul_f32 v[92:93], v[60:61], v[194:195] op_sel_hi:[1,0]
	v_pk_mul_f32 v[90:91], v[58:59], v[194:195] op_sel_hi:[1,0]
	v_pk_mul_f32 v[88:89], v[56:57], v[194:195] op_sel_hi:[1,0]
	v_pk_mul_f32 v[86:87], v[54:55], v[194:195] op_sel_hi:[1,0]
	v_pk_mul_f32 v[84:85], v[52:53], v[194:195] op_sel_hi:[1,0]
	v_cvt_pk_bf16_f32 v36, v149, v150
	v_cvt_pk_bf16_f32 v37, v151, v152
	v_cvt_pk_bf16_f32 v38, v153, v154
	v_cvt_pk_bf16_f32 v39, v155, v156
	s_nop 1
	v_mfma_f32_32x32x16_bf16 v[68:83], v[144:147], v[36:39], v[68:83]
	v_mfma_f32_32x32x16_bf16 v[84:99], v[140:143], v[36:39], v[84:99]
	v_cvt_pk_bf16_f32 v36, v157, v158
	v_cvt_pk_bf16_f32 v37, v159, v160
	v_cvt_pk_bf16_f32 v38, v161, v162
	v_cvt_pk_bf16_f32 v39, v163, v164
	s_nop 1
	v_mfma_f32_32x32x16_bf16 v[68:83], v[136:139], v[36:39], v[68:83]
	v_mfma_f32_32x32x16_bf16 v[84:99], v[132:135], v[36:39], v[84:99]
	v_mul_lo_u32 v36, s56, v222
	v_add_u32_e32 v40, s11, v36
	v_max_i32_e32 v164, 0, v40
	s_waitcnt vmcnt(0)
	v_lshl_add_u32 v38, v164, 7, v180
	s_mov_b32 m0, s57
	v_add_u32_e32 v40, s6, v40
	global_load_lds_dwordx4 v38, s[98:99]
	v_lshl_add_u32 v36, v164, 7, v182
	s_mov_b32 m0, s7
	v_max_i32_e32 v164, 0, v40
	global_load_lds_dwordx4 v36, s[100:101]
	v_readlane_b32 s7, v254, 28
	v_lshl_add_u32 v38, v164, 7, v180
	s_mov_b32 m0, s7
	v_readlane_b32 s7, v254, 29
	v_add_u32_e32 v40, s6, v40
	global_load_lds_dwordx4 v38, s[98:99]
	v_lshl_add_u32 v36, v164, 7, v182
	s_mov_b32 m0, s7
	v_max_i32_e32 v164, 0, v40
	global_load_lds_dwordx4 v36, s[100:101]
	v_lshl_add_u32 v38, v164, 7, v180
	s_mov_b32 m0, s15
	v_lshl_add_u32 v36, v164, 7, v182
	global_load_lds_dwordx4 v38, s[98:99]
	s_mov_b32 m0, s17
	v_sub_u32_e32 v52, v199, v223
	global_load_lds_dwordx4 v36, s[100:101]
	v_add_u32_e32 v36, s6, v40
	v_max_i32_e32 v164, 0, v36
	v_lshl_add_u32 v38, v164, 7, v180
	s_mov_b32 m0, s21
	v_readlane_b32 s6, v254, 30
	global_load_lds_dwordx4 v38, s[98:99]
	v_lshl_add_u32 v36, v164, 7, v182
	s_mov_b32 m0, s6
	v_mov_b32_e32 v53, v224
	global_load_lds_dwordx4 v36, s[100:101]
	ds_read_b128 v[160:163], v225
	ds_read_b128 v[156:159], v226
	ds_read_b128 v[152:155], v227
	ds_read_b128 v[148:151], v228
	s_waitcnt vmcnt(0)
	ds_read_b64_tr_b16 v[144:145], v229 offset:8192
	ds_read_b64_tr_b16 v[146:147], v229 offset:9216
	ds_read_b64_tr_b16 v[140:141], v229 offset:8256
	ds_read_b64_tr_b16 v[142:143], v229 offset:9280
	ds_read_b64_tr_b16 v[136:137], v229 offset:10240
	ds_read_b64_tr_b16 v[138:139], v229 offset:11264
	ds_read_b64_tr_b16 v[132:133], v229 offset:10304
	ds_read_b64_tr_b16 v[134:135], v229 offset:11328
	s_waitcnt lgkmcnt(0)
; __device__ __forceinline__ unsigned pk2(float lo, float hi) { return pg8::cvt_pk_bf16(lo, hi); }
; #define ATT_LOAD_Q(dst, J, set) do { const int qp_ = (J).pos0 + (32 * (set) + qc) * (J).d; _Pragma("unroll") for (int kk_ = 0; kk_ < 4; ++kk_) dst[kk_] = gld<bf16x8>(Qa + ((J).hb + (size_t)qp_) * 64 + 8 * h + 16 * kk_); } while (0)
; __device__ __forceinline__ void att_block(const bf16x8 (&kf)[4], const bf16x8 (&qf)[4], const bf16x8 (&va)[4], f32x16& o0, f32x16& o1, float& mrun, float& lrun, bool domask, int lo_, int hi_) {
;     ...
; #pragma unroll
;     for (int i = 0; i < 16; ++i) st[i] = 0.f;
; #pragma unroll
;     for (int kk = 0; kk < 4; ++kk) st = __builtin_amdgcn_mfma_f32_32x32x16_bf16(kf[kk], qf[kk], st, 0, 0, 0);
;     if (domask) {
;         asm volatile("" : "+v"(lo_), "+v"(hi_));
; #pragma unroll
;         for (int i = 0; i < 16; ++i) { const int ci = (i & 3) + 8 * (i >> 2); st[i] = ((ci - lo_) | (hi_ - ci)) < 0 ? -INFINITY : st[i]; }
;     }
;     float bmax = -INFINITY;
; #pragma unroll
;     for (int i = 0; i < 16; ++i) bmax = fmaxf(bmax, st[i]);
;     bmax = fmaxf(bmax, __shfl_xor(bmax, 32));
;     const float mnew = fmaxf(mrun, bmax);
;     float lsum = 0.f;
; #pragma unroll
;     for (int i = 0; i < 16; ++i) { st[i] = __builtin_amdgcn_exp2f(st[i] - mnew); lsum += st[i]; }
;     lsum += __shfl_xor(lsum, 32);
;     const float alpha = __builtin_amdgcn_exp2f(mrun - mnew);
;     lrun = lrun * alpha + lsum; mrun = mnew;
; #pragma unroll
;     for (int i = 0; i < 16; ++i) { o0[i] *= alpha; o1[i] *= alpha; }
; #pragma unroll
;     for (int s = 0; s < 2; ++s) { v4u w; w.x = pk2(st[8 * s], st[8 * s + 1]); w.y = pk2(st[8 * s + 2], st[8 * s + 3]); w.z = pk2(st[8 * s + 4], st[8 * s + 5]); w.w = pk2(st[8 * s + 6], st[8 * s + 7]);
;         const bf16x8 pb = __builtin_bit_cast(bf16x8, w);
;         o0 = __builtin_amdgcn_mfma_f32_32x32x16_bf16(va[2 * s], pb, o0, 0, 0, 0);
;         o1 = __builtin_amdgcn_mfma_f32_32x32x16_bf16(va[2 * s + 1], pb, o1, 0, 0, 0); }
; __device__ __forceinline__ void att_phase(unsigned char* ws, LAS unsigned char* lds, int lane, int wave, int G) {
;     ...
;                 att_block(kf, qfA, va, oA0, oA1, mA, lA, kb == 0 || kb == 4 || kminA > 32 * kb, mloA - 4 * h - 32 * kb, qc + 128 - 4 * h - 32 * kb);
;                 if (kb == 4 && hn) ATT_LOAD_Q(qfA, N, 0);
	v_mfma_f32_32x32x16_bf16 v[36:51], v[160:163], v[128:131], 0
	s_nop 0
	v_mfma_f32_32x32x16_bf16 v[36:51], v[156:159], v[124:127], v[36:51]
	v_mfma_f32_32x32x16_bf16 v[36:51], v[152:155], v[120:123], v[36:51]
	v_mfma_f32_32x32x16_bf16 v[36:51], v[148:151], v[116:119], v[36:51]
	s_nop 11
	v_cmp_le_i32_e32 vcc, 0, v53
	v_cmp_le_i32_e64 s[24:25], 1, v53
	v_cmp_le_i32_e64 s[26:27], 2, v53
	v_cmp_le_i32_e64 s[28:29], 3, v53
	v_cndmask_b32_e32 v36, v211, v36, vcc
	v_cmp_le_i32_e32 vcc, 8, v53
	v_cndmask_b32_e64 v37, v211, v37, s[24:25]
	v_cmp_le_i32_e64 s[24:25], 9, v53
	v_cndmask_b32_e64 v38, v211, v38, s[26:27]
	v_cmp_le_i32_e64 s[26:27], 10, v53
	v_cndmask_b32_e64 v39, v211, v39, s[28:29]
	v_cmp_le_i32_e64 s[28:29], 11, v53
	v_cndmask_b32_e32 v40, v211, v40, vcc
	v_cmp_le_i32_e32 vcc, 16, v53
	v_cndmask_b32_e64 v41, v211, v41, s[24:25]
	v_cmp_le_i32_e64 s[24:25], 17, v53
	v_cndmask_b32_e64 v42, v211, v42, s[26:27]
	v_cmp_le_i32_e64 s[26:27], 18, v53
	v_cndmask_b32_e64 v43, v211, v43, s[28:29]
	v_cmp_le_i32_e64 s[28:29], 19, v53
	v_cndmask_b32_e32 v44, v211, v44, vcc
	v_cmp_le_i32_e32 vcc, 24, v53
	v_cndmask_b32_e64 v45, v211, v45, s[24:25]
	v_cmp_le_i32_e64 s[24:25], 25, v53
	v_cndmask_b32_e64 v46, v211, v46, s[26:27]
	v_cmp_le_i32_e64 s[26:27], 26, v53
	v_cndmask_b32_e64 v47, v211, v47, s[28:29]
	v_cmp_le_i32_e64 s[28:29], 27, v53
	v_cndmask_b32_e32 v48, v211, v48, vcc
	v_cndmask_b32_e64 v49, v211, v49, s[24:25]
	v_cndmask_b32_e64 v50, v211, v50, s[26:27]
	v_cndmask_b32_e64 v51, v211, v51, s[28:29]
	s_nop 0
	v_max3_f32 v52, v36, s58, v37
	v_max3_f32 v52, v52, v38, v39
	v_max3_f32 v52, v52, v40, v41
	v_max3_f32 v52, v52, v42, v43
	v_max3_f32 v52, v52, v44, v45
	v_max3_f32 v52, v52, v46, v47
	v_max3_f32 v52, v52, v48, v49
	v_max3_f32 v52, v52, v50, v51
	ds_bpermute_b32 v53, v201, v52
	s_andn2_b64 vcc, exec, s[2:3]
	s_waitcnt lgkmcnt(0)
	v_max3_f32 v200, v202, v52, v53
	v_sub_f32_e32 v36, v36, v200
	v_exp_f32_e32 v164, v36
	v_sub_f32_e32 v37, v37, v200
	v_exp_f32_e32 v166, v37
	v_sub_f32_e32 v37, v38, v200
	v_exp_f32_e32 v167, v37
	v_sub_f32_e32 v37, v39, v200
	v_exp_f32_e32 v199, v37
	v_sub_f32_e32 v37, v40, v200
	v_add_f32_e32 v36, 0, v164
	v_exp_f32_e32 v248, v37
	v_sub_f32_e32 v37, v41, v200
	v_add_f32_e32 v36, v166, v36
	v_exp_f32_e32 v249, v37
	v_sub_f32_e32 v37, v42, v200
	v_add_f32_e32 v36, v167, v36
	v_exp_f32_e32 v250, v37
	v_sub_f32_e32 v37, v43, v200
	v_add_f32_e32 v36, v199, v36
	v_exp_f32_e32 v251, v37
	v_sub_f32_e32 v37, v44, v200
	v_add_f32_e32 v36, v248, v36
	v_exp_f32_e32 v252, v37
	v_sub_f32_e32 v37, v45, v200
	v_add_f32_e32 v36, v249, v36
	v_exp_f32_e32 v203, v37
	v_sub_f32_e32 v37, v46, v200
	v_add_f32_e32 v36, v250, v36
	v_exp_f32_e32 v168, v37
	v_sub_f32_e32 v37, v47, v200
	v_add_f32_e32 v36, v251, v36
	v_exp_f32_e32 v169, v37
	v_sub_f32_e32 v37, v48, v200
	v_add_f32_e32 v36, v252, v36
	v_exp_f32_e32 v212, v37
	v_sub_f32_e32 v37, v49, v200
	v_add_f32_e32 v36, v203, v36
	v_exp_f32_e32 v209, v37
	v_sub_f32_e32 v37, v50, v200
	v_add_f32_e32 v36, v168, v36
	v_exp_f32_e32 v197, v37
	v_sub_f32_e32 v37, v51, v200
	v_add_f32_e32 v36, v169, v36
	v_exp_f32_e32 v195, v37
	v_add_f32_e32 v36, v212, v36
	v_add_f32_e32 v36, v209, v36
	v_add_f32_e32 v36, v197, v36
	v_add_f32_e32 v246, v195, v36
	v_sub_f32_e32 v36, v202, v200
	v_exp_f32_e32 v202, v36
	ds_bpermute_b32 v247, v201, v246
	v_pk_mul_f32 v[66:67], v[18:19], v[202:203] op_sel_hi:[1,0]
	v_pk_mul_f32 v[64:65], v[16:17], v[202:203] op_sel_hi:[1,0]
	v_pk_mul_f32 v[62:63], v[14:15], v[202:203] op_sel_hi:[1,0]
	v_pk_mul_f32 v[60:61], v[12:13], v[202:203] op_sel_hi:[1,0]
	v_pk_mul_f32 v[58:59], v[10:11], v[202:203] op_sel_hi:[1,0]
	v_pk_mul_f32 v[56:57], v[8:9], v[202:203] op_sel_hi:[1,0]
	v_pk_mul_f32 v[54:55], v[6:7], v[202:203] op_sel_hi:[1,0]
	v_pk_mul_f32 v[52:53], v[4:5], v[202:203] op_sel_hi:[1,0]
	v_pk_mul_f32 v[50:51], v[34:35], v[202:203] op_sel_hi:[1,0]
	v_pk_mul_f32 v[48:49], v[32:33], v[202:203] op_sel_hi:[1,0]
	v_pk_mul_f32 v[46:47], v[30:31], v[202:203] op_sel_hi:[1,0]
	v_pk_mul_f32 v[44:45], v[28:29], v[202:203] op_sel_hi:[1,0]
	v_pk_mul_f32 v[42:43], v[26:27], v[202:203] op_sel_hi:[1,0]
	v_pk_mul_f32 v[40:41], v[24:25], v[202:203] op_sel_hi:[1,0]
	v_pk_mul_f32 v[38:39], v[22:23], v[202:203] op_sel_hi:[1,0]
	v_pk_mul_f32 v[36:37], v[20:21], v[202:203] op_sel_hi:[1,0]
	v_cvt_pk_bf16_f32 v4, v164, v166
	v_cvt_pk_bf16_f32 v5, v167, v199
	v_cvt_pk_bf16_f32 v6, v248, v249
	v_cvt_pk_bf16_f32 v7, v250, v251
	s_nop 1
	v_mfma_f32_32x32x16_bf16 v[52:67], v[144:147], v[4:7], v[52:67]
	v_mfma_f32_32x32x16_bf16 v[36:51], v[140:143], v[4:7], v[36:51]
	v_cvt_pk_bf16_f32 v4, v252, v203
	v_cvt_pk_bf16_f32 v5, v168, v169
	v_cvt_pk_bf16_f32 v6, v212, v209
	v_cvt_pk_bf16_f32 v7, v197, v195
	s_nop 1
	v_mfma_f32_32x32x16_bf16 v[52:67], v[136:139], v[4:7], v[52:67]
	v_mfma_f32_32x32x16_bf16 v[36:51], v[132:135], v[4:7], v[36:51]
	v_cndmask_b32_e64 v4, 0, 1, s[2:3]
	v_cmp_ne_u32_e64 s[6:7], 1, v4
	s_cbranch_vccnz .LBB0_92
	v_ashrrev_i32_e32 v199, 31, v198
	v_lshl_add_u64 v[4:5], s[0:1], 0, v[198:199]
	v_lshlrev_b64 v[4:5], 7, v[4:5]
	v_lshl_add_u64 v[4:5], v[186:187], 0, v[4:5]
	global_load_dwordx4 v[128:131], v[4:5], off
	global_load_dwordx4 v[124:127], v[4:5], off offset:32
	global_load_dwordx4 v[120:123], v[4:5], off offset:64
	global_load_dwordx4 v[116:119], v[4:5], off offset:96
; __device__ __forceinline__ unsigned pk2(float lo, float hi) { return pg8::cvt_pk_bf16(lo, hi); }
; __device__ __forceinline__ void att_block(const bf16x8 (&kf)[4], const bf16x8 (&qf)[4], const bf16x8 (&va)[4], f32x16& o0, f32x16& o1, float& mrun, float& lrun, bool domask, int lo_, int hi_) {
;     ...
; #pragma unroll
;     for (int i = 0; i < 16; ++i) st[i] = 0.f;
; #pragma unroll
;     for (int kk = 0; kk < 4; ++kk) st = __builtin_amdgcn_mfma_f32_32x32x16_bf16(kf[kk], qf[kk], st, 0, 0, 0);
;     if (domask) {
;         asm volatile("" : "+v"(lo_), "+v"(hi_));
; #pragma unroll
;         for (int i = 0; i < 16; ++i) { const int ci = (i & 3) + 8 * (i >> 2); st[i] = ((ci - lo_) | (hi_ - ci)) < 0 ? -INFINITY : st[i]; }
;     }
;     float bmax = -INFINITY;
; #pragma unroll
;     for (int i = 0; i < 16; ++i) bmax = fmaxf(bmax, st[i]);
;     bmax = fmaxf(bmax, __shfl_xor(bmax, 32));
;     const float mnew = fmaxf(mrun, bmax);
;     float lsum = 0.f;
; #pragma unroll
;     for (int i = 0; i < 16; ++i) { st[i] = __builtin_amdgcn_exp2f(st[i] - mnew); lsum += st[i]; }
;     lsum += __shfl_xor(lsum, 32);
;     const float alpha = __builtin_amdgcn_exp2f(mrun - mnew);
;     lrun = lrun * alpha + lsum; mrun = mnew;
; #pragma unroll
;     for (int i = 0; i < 16; ++i) { o0[i] *= alpha; o1[i] *= alpha; }
; #pragma unroll
;     for (int s = 0; s < 2; ++s) { v4u w; w.x = pk2(st[8 * s], st[8 * s + 1]); w.y = pk2(st[8 * s + 2], st[8 * s + 3]); w.z = pk2(st[8 * s + 4], st[8 * s + 5]); w.w = pk2(st[8 * s + 6], st[8 * s + 7]);
;         const bf16x8 pb = __builtin_bit_cast(bf16x8, w);
;         o0 = __builtin_amdgcn_mfma_f32_32x32x16_bf16(va[2 * s], pb, o0, 0, 0, 0);
;         o1 = __builtin_amdgcn_mfma_f32_32x32x16_bf16(va[2 * s + 1], pb, o1, 0, 0, 0); }
; __device__ __forceinline__ void att_phase(unsigned char* ws, LAS unsigned char* lds, int lane, int wave, int G) {
;     ...
;             if (kb < 5) ATT_DMA_KV(P, kb + 1, sb ^ 1);
;             else if (hn) ATT_DMA_KV(N, 0, sb ^ 1);
.LBB0_92:
	v_mfma_f32_32x32x16_bf16 v[4:19], v[160:163], v[112:115], 0
	s_cmpk_lt_i32 s14, 0x61
	v_mfma_f32_32x32x16_bf16 v[4:19], v[156:159], v[108:111], v[4:19]
	v_mfma_f32_32x32x16_bf16 v[4:19], v[152:155], v[104:107], v[4:19]
	v_mfma_f32_32x32x16_bf16 v[4:19], v[148:151], v[100:103], v[4:19]
	s_cbranch_scc1 .LBB0_94
	v_sub_u32_e32 v20, v237, v220
	v_mov_b32_e32 v21, v221
	s_nop 0
	s_nop 1
	v_cmp_ge_i32_e32 vcc, 0, v20
	v_cmp_ge_i32_e64 s[24:25], 1, v20
	v_cmp_ge_i32_e64 s[26:27], 2, v20
	v_cmp_ge_i32_e64 s[28:29], 3, v20
	s_nop 1
	v_cndmask_b32_e32 v4, v211, v4, vcc
	v_cmp_ge_i32_e32 vcc, 8, v20
	v_cndmask_b32_e64 v5, v211, v5, s[24:25]
	v_cmp_ge_i32_e64 s[24:25], 9, v20
	v_cndmask_b32_e64 v6, v211, v6, s[26:27]
	v_cmp_ge_i32_e64 s[26:27], 10, v20
	v_cndmask_b32_e64 v7, v211, v7, s[28:29]
	v_cmp_ge_i32_e64 s[28:29], 11, v20
	v_cndmask_b32_e32 v8, v211, v8, vcc
	v_cmp_ge_i32_e32 vcc, 16, v20
	v_cndmask_b32_e64 v9, v211, v9, s[24:25]
	v_cmp_ge_i32_e64 s[24:25], 17, v20
	v_cndmask_b32_e64 v10, v211, v10, s[26:27]
	v_cmp_ge_i32_e64 s[26:27], 18, v20
	v_cndmask_b32_e64 v11, v211, v11, s[28:29]
	v_cmp_ge_i32_e64 s[28:29], 19, v20
	v_cndmask_b32_e32 v12, v211, v12, vcc
	v_cmp_ge_i32_e32 vcc, 24, v20
	v_cndmask_b32_e64 v13, v211, v13, s[24:25]
	v_cmp_ge_i32_e64 s[24:25], 25, v20
	v_cndmask_b32_e64 v14, v211, v14, s[26:27]
	v_cmp_ge_i32_e64 s[26:27], 26, v20
	v_cndmask_b32_e64 v15, v211, v15, s[28:29]
	v_cmp_ge_i32_e64 s[28:29], 27, v20
	v_cndmask_b32_e32 v16, v211, v16, vcc
	v_cndmask_b32_e64 v17, v211, v17, s[24:25]
	v_cndmask_b32_e64 v18, v211, v18, s[26:27]
	v_cndmask_b32_e64 v19, v211, v19, s[28:29]
	s_nop 0
	s_nop 1
.LBB0_94:
	s_mov_b32 s14, 0xff800000
	s_nop 9
	v_max3_f32 v20, v4, s14, v5
	v_max3_f32 v20, v20, v6, v7
	v_max3_f32 v20, v20, v8, v9
	v_max3_f32 v20, v20, v10, v11
	v_max3_f32 v20, v20, v12, v13
	v_max3_f32 v20, v20, v14, v15
	v_max3_f32 v20, v20, v16, v17
	v_max3_f32 v20, v20, v18, v19
	ds_bpermute_b32 v21, v201, v20
	s_waitcnt lgkmcnt(0)
	s_waitcnt lgkmcnt(0)
	v_max3_f32 v151, v245, v20, v21
	v_sub_f32_e32 v4, v4, v151
	v_exp_f32_e32 v152, v4
	v_sub_f32_e32 v5, v5, v151
	v_exp_f32_e32 v153, v5
	v_sub_f32_e32 v5, v6, v151
	v_exp_f32_e32 v154, v5
	v_sub_f32_e32 v5, v7, v151
	v_exp_f32_e32 v155, v5
	v_sub_f32_e32 v5, v8, v151
	v_add_f32_e32 v4, 0, v152
	v_exp_f32_e32 v156, v5
	v_sub_f32_e32 v5, v9, v151
	v_add_f32_e32 v4, v153, v4
	v_exp_f32_e32 v157, v5
	v_sub_f32_e32 v5, v10, v151
	v_add_f32_e32 v4, v154, v4
	v_exp_f32_e32 v158, v5
	v_sub_f32_e32 v5, v11, v151
	v_add_f32_e32 v4, v155, v4
	v_exp_f32_e32 v159, v5
	v_sub_f32_e32 v5, v12, v151
	v_add_f32_e32 v4, v156, v4
	v_exp_f32_e32 v160, v5
	v_sub_f32_e32 v5, v13, v151
	v_add_f32_e32 v4, v157, v4
	v_exp_f32_e32 v161, v5
	v_sub_f32_e32 v5, v14, v151
	v_add_f32_e32 v4, v158, v4
	v_exp_f32_e32 v162, v5
	v_sub_f32_e32 v5, v15, v151
	v_add_f32_e32 v4, v159, v4
	v_exp_f32_e32 v163, v5
	v_sub_f32_e32 v5, v16, v151
	v_add_f32_e32 v4, v160, v4
	v_exp_f32_e32 v164, v5
	v_sub_f32_e32 v5, v17, v151
	v_add_f32_e32 v4, v161, v4
	v_exp_f32_e32 v166, v5
	v_sub_f32_e32 v5, v18, v151
	v_add_f32_e32 v4, v162, v4
	v_exp_f32_e32 v167, v5
	v_sub_f32_e32 v5, v19, v151
	v_add_f32_e32 v4, v163, v4
	v_exp_f32_e32 v168, v5
	v_add_f32_e32 v4, v164, v4
	v_add_f32_e32 v4, v166, v4
	v_add_f32_e32 v4, v167, v4
	v_add_f32_e32 v149, v168, v4
	v_sub_f32_e32 v4, v245, v151
	v_exp_f32_e32 v148, v4
	ds_bpermute_b32 v150, v201, v149
	v_pk_mul_f32 v[34:35], v[82:83], v[148:149] op_sel_hi:[1,0]
	v_pk_mul_f32 v[32:33], v[80:81], v[148:149] op_sel_hi:[1,0]
	v_pk_mul_f32 v[30:31], v[78:79], v[148:149] op_sel_hi:[1,0]
	v_pk_mul_f32 v[28:29], v[76:77], v[148:149] op_sel_hi:[1,0]
	v_pk_mul_f32 v[26:27], v[74:75], v[148:149] op_sel_hi:[1,0]
	v_pk_mul_f32 v[24:25], v[72:73], v[148:149] op_sel_hi:[1,0]
	v_pk_mul_f32 v[22:23], v[70:71], v[148:149] op_sel_hi:[1,0]
	v_pk_mul_f32 v[20:21], v[68:69], v[148:149] op_sel_hi:[1,0]
	v_pk_mul_f32 v[18:19], v[98:99], v[148:149] op_sel_hi:[1,0]
	v_pk_mul_f32 v[16:17], v[96:97], v[148:149] op_sel_hi:[1,0]
	v_pk_mul_f32 v[14:15], v[94:95], v[148:149] op_sel_hi:[1,0]
	v_pk_mul_f32 v[12:13], v[92:93], v[148:149] op_sel_hi:[1,0]
	v_pk_mul_f32 v[10:11], v[90:91], v[148:149] op_sel_hi:[1,0]
	v_pk_mul_f32 v[8:9], v[88:89], v[148:149] op_sel_hi:[1,0]
	v_pk_mul_f32 v[6:7], v[86:87], v[148:149] op_sel_hi:[1,0]
	v_pk_mul_f32 v[4:5], v[84:85], v[148:149] op_sel_hi:[1,0]
	v_cvt_pk_bf16_f32 v68, v152, v153
	v_cvt_pk_bf16_f32 v69, v154, v155
	v_cvt_pk_bf16_f32 v70, v156, v157
	v_cvt_pk_bf16_f32 v71, v158, v159
	s_nop 1
	v_mfma_f32_32x32x16_bf16 v[20:35], v[144:147], v[68:71], v[20:35]
	v_mfma_f32_32x32x16_bf16 v[4:19], v[140:143], v[68:71], v[4:19]
	v_cvt_pk_bf16_f32 v68, v160, v161
	v_cvt_pk_bf16_f32 v69, v162, v163
	v_cvt_pk_bf16_f32 v70, v164, v166
	v_cvt_pk_bf16_f32 v71, v167, v168
	s_nop 1
	v_mfma_f32_32x32x16_bf16 v[20:35], v[136:139], v[68:71], v[20:35]
	v_mfma_f32_32x32x16_bf16 v[4:19], v[132:135], v[68:71], v[4:19]
	s_waitcnt vmcnt(0)
	s_and_b64 vcc, exec, s[6:7]
	s_cbranch_vccnz .LBB0_96
	v_add_u32_e32 v68, 0xffffff80, v191
	v_mul_lo_u32 v68, s52, v68
	v_add_u32_e32 v72, s53, v68
	v_max_i32_e32 v164, 0, v72
	s_lshl_b32 s14, s52, 3
	s_mov_b32 m0, s33
	v_lshl_add_u32 v70, v164, 7, v180
	v_add_u32_e32 v72, s14, v72
	global_load_lds_dwordx4 v70, s[30:31]
	v_lshl_add_u32 v68, v164, 7, v182
	s_mov_b32 m0, s44
	v_max_i32_e32 v164, 0, v72
	global_load_lds_dwordx4 v68, s[34:35]
	v_lshl_add_u32 v70, v164, 7, v180
	s_mov_b32 m0, s66
	v_add_u32_e32 v72, s14, v72
	global_load_lds_dwordx4 v70, s[30:31]
	v_lshl_add_u32 v68, v164, 7, v182
	s_mov_b32 m0, s67
	v_max_i32_e32 v164, 0, v72
	global_load_lds_dwordx4 v68, s[34:35]
	v_lshl_add_u32 v70, v164, 7, v180
	s_mov_b32 m0, s48
	v_lshl_add_u32 v68, v164, 7, v182
	global_load_lds_dwordx4 v70, s[30:31]
	s_mov_b32 m0, s49
	s_nop 0
	global_load_lds_dwordx4 v68, s[34:35]
	v_add_u32_e32 v68, s14, v72
	v_max_i32_e32 v164, 0, v68
	v_lshl_add_u32 v70, v164, 7, v180
	s_mov_b32 m0, s72
	v_readlane_b32 s14, v254, 27
	global_load_lds_dwordx4 v70, s[30:31]
	v_lshl_add_u32 v68, v164, 7, v182
	s_mov_b32 m0, s14
	s_nop 0
	global_load_lds_dwordx4 v68, s[34:35]
; __device__ __forceinline__ unsigned pk2(float lo, float hi) { return pg8::cvt_pk_bf16(lo, hi); }
; #define ATT_LOAD_Q(dst, J, set) do { const int qp_ = (J).pos0 + (32 * (set) + qc) * (J).d; _Pragma("unroll") for (int kk_ = 0; kk_ < 4; ++kk_) dst[kk_] = gld<bf16x8>(Qa + ((J).hb + (size_t)qp_) * 64 + 8 * h + 16 * kk_); } while (0)
; __device__ __forceinline__ void att_block(const bf16x8 (&kf)[4], const bf16x8 (&qf)[4], const bf16x8 (&va)[4], f32x16& o0, f32x16& o1, float& mrun, float& lrun, bool domask, int lo_, int hi_) {
;     ...
; #pragma unroll
;     for (int i = 0; i < 16; ++i) st[i] = 0.f;
; #pragma unroll
;     for (int kk = 0; kk < 4; ++kk) st = __builtin_amdgcn_mfma_f32_32x32x16_bf16(kf[kk], qf[kk], st, 0, 0, 0);
;     if (domask) {
;         asm volatile("" : "+v"(lo_), "+v"(hi_));
; #pragma unroll
;         for (int i = 0; i < 16; ++i) { const int ci = (i & 3) + 8 * (i >> 2); st[i] = ((ci - lo_) | (hi_ - ci)) < 0 ? -INFINITY : st[i]; }
;     }
;     float bmax = -INFINITY;
; #pragma unroll
;     for (int i = 0; i < 16; ++i) bmax = fmaxf(bmax, st[i]);
;     bmax = fmaxf(bmax, __shfl_xor(bmax, 32));
;     const float mnew = fmaxf(mrun, bmax);
;     float lsum = 0.f;
; #pragma unroll
;     for (int i = 0; i < 16; ++i) { st[i] = __builtin_amdgcn_exp2f(st[i] - mnew); lsum += st[i]; }
;     lsum += __shfl_xor(lsum, 32);
;     const float alpha = __builtin_amdgcn_exp2f(mrun - mnew);
;     lrun = lrun * alpha + lsum; mrun = mnew;
; #pragma unroll
;     for (int i = 0; i < 16; ++i) { o0[i] *= alpha; o1[i] *= alpha; }
; #pragma unroll
;     for (int s = 0; s < 2; ++s) { v4u w; w.x = pk2(st[8 * s], st[8 * s + 1]); w.y = pk2(st[8 * s + 2], st[8 * s + 3]); w.z = pk2(st[8 * s + 4], st[8 * s + 5]); w.w = pk2(st[8 * s + 6], st[8 * s + 7]);
;         const bf16x8 pb = __builtin_bit_cast(bf16x8, w);
;         o0 = __builtin_amdgcn_mfma_f32_32x32x16_bf16(va[2 * s], pb, o0, 0, 0, 0);
;         o1 = __builtin_amdgcn_mfma_f32_32x32x16_bf16(va[2 * s + 1], pb, o1, 0, 0, 0); }
; __device__ __forceinline__ void att_phase(unsigned char* ws, LAS unsigned char* lds, int lane, int wave, int G) {
;     ...
;                 att_block(kf, qfB, va, oB0, oB1, mB, lB, kb == 1 || kb == 5 || kminB > 32 * (kb - 1), mloB - 4 * h - 32 * (kb - 1), qc + 128 - 4 * h - 32 * (kb - 1));
;                 if (kb == 5 && hn) ATT_LOAD_Q(qfB, N, 1);
.LBB0_96:
	ds_read_b128 v[68:71], v225 offset:4096
	ds_read_b128 v[132:135], v226 offset:4096
	ds_read_b128 v[136:139], v227 offset:4096
	ds_read_b128 v[140:143], v228 offset:4096
	s_waitcnt vmcnt(0)
	ds_read_b64_tr_b16 v[92:93], v229 offset:12288
	ds_read_b64_tr_b16 v[94:95], v229 offset:13312
	ds_read_b64_tr_b16 v[86:87], v229 offset:13376
	ds_read_b64_tr_b16 v[84:85], v229 offset:12352
	s_waitcnt lgkmcnt(0)
	v_mfma_f32_32x32x16_bf16 v[68:83], v[68:71], v[112:115], 0
	v_sub_u32_e32 v144, v237, v223
	v_mov_b32_e32 v145, v224
	ds_read_b64_tr_b16 v[96:97], v229 offset:14336
	ds_read_b64_tr_b16 v[98:99], v229 offset:15360
	ds_read_b64_tr_b16 v[90:91], v229 offset:15424
	ds_read_b64_tr_b16 v[88:89], v229 offset:14400
	s_mov_b32 s14, 0xff800000
	v_mfma_f32_32x32x16_bf16 v[68:83], v[132:135], v[108:111], v[68:83]
	v_mfma_f32_32x32x16_bf16 v[68:83], v[136:139], v[104:107], v[68:83]
	v_mfma_f32_32x32x16_bf16 v[68:83], v[140:143], v[100:103], v[68:83]
	s_nop 11
	v_cmp_le_i32_e32 vcc, 0, v145
	v_cmp_le_i32_e64 s[24:25], 1, v145
	v_cmp_le_i32_e64 s[26:27], 2, v145
	v_cmp_le_i32_e64 s[28:29], 3, v145
	v_cndmask_b32_e32 v68, v211, v68, vcc
	v_cmp_le_i32_e32 vcc, 8, v145
	v_cndmask_b32_e64 v69, v211, v69, s[24:25]
	v_cmp_le_i32_e64 s[24:25], 9, v145
	v_cndmask_b32_e64 v70, v211, v70, s[26:27]
	v_cmp_le_i32_e64 s[26:27], 10, v145
	v_cndmask_b32_e64 v71, v211, v71, s[28:29]
	v_cmp_le_i32_e64 s[28:29], 11, v145
	v_cndmask_b32_e32 v72, v211, v72, vcc
	v_cmp_le_i32_e32 vcc, 16, v145
	v_cndmask_b32_e64 v73, v211, v73, s[24:25]
	v_cmp_le_i32_e64 s[24:25], 17, v145
	v_cndmask_b32_e64 v74, v211, v74, s[26:27]
	v_cmp_le_i32_e64 s[26:27], 18, v145
	v_cndmask_b32_e64 v75, v211, v75, s[28:29]
	v_cmp_le_i32_e64 s[28:29], 19, v145
	v_cndmask_b32_e32 v132, v211, v76, vcc
	v_cmp_le_i32_e32 vcc, 24, v145
	v_cndmask_b32_e64 v77, v211, v77, s[24:25]
	v_cmp_le_i32_e64 s[24:25], 25, v145
	v_cndmask_b32_e64 v78, v211, v78, s[26:27]
	v_cmp_le_i32_e64 s[26:27], 26, v145
	v_cndmask_b32_e64 v79, v211, v79, s[28:29]
	v_cmp_le_i32_e64 s[28:29], 27, v145
	v_cndmask_b32_e32 v80, v211, v80, vcc
	v_cndmask_b32_e64 v81, v211, v81, s[24:25]
	v_cndmask_b32_e64 v82, v211, v82, s[26:27]
	v_cndmask_b32_e64 v83, v211, v83, s[28:29]
	s_nop 0
	s_nop 1
	s_nop 1
	s_nop 0
	v_max3_f32 v76, v68, s14, v69
	v_max3_f32 v76, v76, v70, v71
	v_max3_f32 v76, v76, v72, v73
	v_max3_f32 v76, v76, v74, v75
	v_max3_f32 v76, v76, v132, v77
	v_max3_f32 v76, v76, v78, v79
	v_max3_f32 v76, v76, v80, v81
	v_max3_f32 v76, v76, v82, v83
	ds_bpermute_b32 v133, v201, v76
	s_and_b64 vcc, exec, s[6:7]
	s_waitcnt lgkmcnt(0)
	v_max3_f32 v76, v151, v76, v133
	v_sub_f32_e32 v68, v68, v76
	v_exp_f32_e32 v68, v68
	v_sub_f32_e32 v69, v69, v76
	v_exp_f32_e32 v69, v69
	v_sub_f32_e32 v70, v70, v76
	v_exp_f32_e32 v70, v70
	v_sub_f32_e32 v71, v71, v76
	v_exp_f32_e32 v71, v71
	v_sub_f32_e32 v72, v72, v76
	v_add_f32_e32 v133, 0, v68
	v_exp_f32_e32 v72, v72
	v_sub_f32_e32 v73, v73, v76
	v_add_f32_e32 v133, v69, v133
	v_exp_f32_e32 v73, v73
	v_sub_f32_e32 v74, v74, v76
	v_add_f32_e32 v133, v70, v133
	v_exp_f32_e32 v74, v74
	v_sub_f32_e32 v75, v75, v76
	v_add_f32_e32 v133, v71, v133
	v_exp_f32_e32 v75, v75
	v_sub_f32_e32 v132, v132, v76
	v_add_f32_e32 v133, v72, v133
	v_exp_f32_e32 v132, v132
	v_sub_f32_e32 v77, v77, v76
	v_add_f32_e32 v133, v73, v133
	v_exp_f32_e32 v77, v77
	v_sub_f32_e32 v78, v78, v76
	v_add_f32_e32 v133, v74, v133
	v_exp_f32_e32 v134, v78
	v_add_f32_e32 v78, v75, v133
	v_add_f32_e32 v78, v132, v78
	v_add_f32_e32 v78, v77, v78
	v_add_f32_e32 v133, v134, v78
	v_sub_f32_e32 v78, v79, v76
	v_exp_f32_e32 v79, v78
	v_sub_f32_e32 v78, v80, v76
	v_exp_f32_e32 v80, v78
	v_sub_f32_e32 v78, v151, v76
	v_exp_f32_e32 v78, v78
	v_cvt_pk_bf16_f32 v68, v68, v69
	v_cvt_pk_bf16_f32 v69, v70, v71
	v_cvt_pk_bf16_f32 v70, v72, v73
	v_pk_mul_f32 v[34:35], v[34:35], v[78:79] op_sel_hi:[1,0]
	v_pk_mul_f32 v[32:33], v[32:33], v[78:79] op_sel_hi:[1,0]
	v_pk_mul_f32 v[30:31], v[30:31], v[78:79] op_sel_hi:[1,0]
	v_pk_mul_f32 v[28:29], v[28:29], v[78:79] op_sel_hi:[1,0]
	v_pk_mul_f32 v[26:27], v[26:27], v[78:79] op_sel_hi:[1,0]
	v_pk_mul_f32 v[24:25], v[24:25], v[78:79] op_sel_hi:[1,0]
	v_pk_mul_f32 v[22:23], v[22:23], v[78:79] op_sel_hi:[1,0]
	v_pk_mul_f32 v[20:21], v[20:21], v[78:79] op_sel_hi:[1,0]
	v_pk_mul_f32 v[18:19], v[18:19], v[78:79] op_sel_hi:[1,0]
	v_cvt_pk_bf16_f32 v71, v74, v75
	v_pk_mul_f32 v[16:17], v[16:17], v[78:79] op_sel_hi:[1,0]
	v_pk_mul_f32 v[14:15], v[14:15], v[78:79] op_sel_hi:[1,0]
	v_pk_mul_f32 v[12:13], v[12:13], v[78:79] op_sel_hi:[1,0]
	v_pk_mul_f32 v[10:11], v[10:11], v[78:79] op_sel_hi:[1,0]
	v_pk_mul_f32 v[8:9], v[8:9], v[78:79] op_sel_hi:[1,0]
	v_pk_mul_f32 v[6:7], v[6:7], v[78:79] op_sel_hi:[1,0]
	v_pk_mul_f32 v[4:5], v[4:5], v[78:79] op_sel_hi:[1,0]
	v_mfma_f32_32x32x16_bf16 v[20:35], v[92:95], v[68:71], v[20:35]
	v_sub_f32_e32 v81, v81, v76
	v_sub_f32_e32 v82, v82, v76
	v_exp_f32_e32 v81, v81
	v_exp_f32_e32 v72, v82
	v_add_f32_e32 v74, v79, v133
	v_add_f32_e32 v74, v80, v74
	v_add_f32_e32 v74, v81, v74
	v_mfma_f32_32x32x16_bf16 v[4:19], v[84:87], v[68:71], v[4:19]
	v_sub_f32_e32 v68, v83, v76
	v_exp_f32_e32 v73, v68
	v_cvt_pk_bf16_f32 v68, v132, v77
	v_cvt_pk_bf16_f32 v69, v134, v79
	v_cvt_pk_bf16_f32 v70, v80, v81
	v_cvt_pk_bf16_f32 v71, v72, v73
	v_add_f32_e32 v72, v72, v74
	v_add_f32_e32 v77, v73, v72
	v_mfma_f32_32x32x16_bf16 v[20:35], v[96:99], v[68:71], v[20:35]
	ds_bpermute_b32 v79, v201, v77
	v_mfma_f32_32x32x16_bf16 v[4:19], v[88:91], v[68:71], v[4:19]
	s_cbranch_vccnz .LBB0_98
	v_lshl_add_u32 v68, s52, 5, v198
	v_ashrrev_i32_e32 v69, 31, v68
	v_lshl_add_u64 v[68:69], s[0:1], 0, v[68:69]
	v_lshlrev_b64 v[68:69], 7, v[68:69]
	v_lshl_add_u64 v[68:69], v[186:187], 0, v[68:69]
	global_load_dwordx4 v[112:115], v[68:69], off
	global_load_dwordx4 v[108:111], v[68:69], off offset:32
	global_load_dwordx4 v[104:107], v[68:69], off offset:64
	global_load_dwordx4 v[100:103], v[68:69], off offset:96
